# GEMM K-loops: 12 of the 16 LDS-DMA loads per iteration use the scalar-base (saddr) form with the 32-bit per-lane offset, dropping their 64-bit VALU address adds
# speedup vs baseline: 1.0098x; 1.0087x over previous
.LBB0_411:
	s_add_u32 s30, s2, 0xfff80080
	s_addc_u32 s31, s3, -1
	s_add_i32 s49, 0, 0x10000
	s_cmp_eq_u32 s47, 28
	s_cselect_b32 s37, s41, s31
	s_cselect_b32 s36, s42, s30
	s_cselect_b32 s31, s43, s46
	s_cselect_b32 s30, s44, s45
	s_add_i32 s51, 0, 0x14000
	v_add_u32_e32 v142, s49, v197
	v_add_u32_e32 v172, s51, v197
	ds_read_b128 v[130:133], v142
	ds_read_b128 v[134:137], v142 offset:1024
	ds_read_b128 v[138:141], v142 offset:2048
	ds_read_b128 v[142:145], v142 offset:3072
	ds_read_b128 v[160:163], v172
	ds_read_b128 v[164:167], v172 offset:1024
	ds_read_b128 v[168:171], v172 offset:2048
	ds_read_b128 v[172:175], v172 offset:3072
	s_add_i32 m0, s24, 0xc000
	ds_read_b128 v[176:179], v200
	ds_read_b128 v[180:183], v200 offset:1024
	ds_read_b128 v[184:187], v200 offset:2048
	ds_read_b128 v[188:191], v200 offset:3072
	ds_read_b128 v[192:195], v200 offset:4096
	ds_read_b128 v[202:205], v200 offset:5120
	ds_read_b128 v[206:209], v200 offset:6144
	ds_read_b128 v[216:219], v200 offset:7168
	global_load_lds_dwordx4 v156, s[2:3]
	s_add_i32 m0, s24, 0xe000
	s_nop 0
	global_load_lds_dwordx4 v158, s[2:3]
	s_waitcnt vmcnt(8)
	s_waitcnt lgkmcnt(0)
	s_barrier
	s_setprio 1
	s_waitcnt lgkmcnt(0)
	v_mfma_f32_16x16x32_bf16 v[126:129], v[130:133], v[176:179], v[126:129]
	v_mfma_f32_16x16x32_bf16 v[122:125], v[138:141], v[176:179], v[122:125]
	v_mfma_f32_16x16x32_bf16 v[110:113], v[130:133], v[184:187], v[110:113]
	v_mfma_f32_16x16x32_bf16 v[106:109], v[138:141], v[184:187], v[106:109]
	v_mfma_f32_16x16x32_bf16 v[94:97], v[130:133], v[192:195], v[94:97]
	v_mfma_f32_16x16x32_bf16 v[90:93], v[138:141], v[192:195], v[90:93]
	v_mfma_f32_16x16x32_bf16 v[78:81], v[130:133], v[206:209], v[78:81]
	v_mfma_f32_16x16x32_bf16 v[74:77], v[138:141], v[206:209], v[74:77]
	v_mfma_f32_16x16x32_bf16 v[126:129], v[134:137], v[180:183], v[126:129]
	v_mfma_f32_16x16x32_bf16 v[122:125], v[142:145], v[180:183], v[122:125]
	v_mfma_f32_16x16x32_bf16 v[110:113], v[134:137], v[188:191], v[110:113]
	v_mfma_f32_16x16x32_bf16 v[106:109], v[142:145], v[188:191], v[106:109]
	v_mfma_f32_16x16x32_bf16 v[94:97], v[134:137], v[202:205], v[94:97]
	v_mfma_f32_16x16x32_bf16 v[90:93], v[142:145], v[202:205], v[90:93]
	v_mfma_f32_16x16x32_bf16 v[78:81], v[134:137], v[216:219], v[78:81]
	v_mfma_f32_16x16x32_bf16 v[74:77], v[142:145], v[216:219], v[74:77]
	s_setprio 0
	s_setprio 1
	v_mfma_f32_16x16x32_bf16 v[118:121], v[160:163], v[176:179], v[118:121]
	v_mfma_f32_16x16x32_bf16 v[114:117], v[168:171], v[176:179], v[114:117]
	v_mfma_f32_16x16x32_bf16 v[102:105], v[160:163], v[184:187], v[102:105]
	v_mfma_f32_16x16x32_bf16 v[98:101], v[168:171], v[184:187], v[98:101]
	v_mfma_f32_16x16x32_bf16 v[86:89], v[160:163], v[192:195], v[86:89]
	v_mfma_f32_16x16x32_bf16 v[82:85], v[168:171], v[192:195], v[82:85]
	v_mfma_f32_16x16x32_bf16 v[70:73], v[160:163], v[206:209], v[70:73]
	v_mfma_f32_16x16x32_bf16 v[66:69], v[168:171], v[206:209], v[66:69]
	v_mfma_f32_16x16x32_bf16 v[118:121], v[164:167], v[180:183], v[118:121]
	v_mfma_f32_16x16x32_bf16 v[114:117], v[172:175], v[180:183], v[114:117]
	v_mfma_f32_16x16x32_bf16 v[102:105], v[164:167], v[188:191], v[102:105]
	v_mfma_f32_16x16x32_bf16 v[98:101], v[172:175], v[188:191], v[98:101]
	v_mfma_f32_16x16x32_bf16 v[86:89], v[164:167], v[202:205], v[86:89]
	v_mfma_f32_16x16x32_bf16 v[82:85], v[172:175], v[202:205], v[82:85]
	v_mfma_f32_16x16x32_bf16 v[70:73], v[164:167], v[216:219], v[70:73]
	v_mfma_f32_16x16x32_bf16 v[66:69], v[172:175], v[216:219], v[66:69]
	s_setprio 0
	s_barrier
	s_add_i32 s49, s49, s19
	v_lshl_add_u64 v[220:221], s[30:31], 0, v[0:1]
	s_mov_b32 m0, s49
	ds_read_b128 v[176:179], v200 offset:16384
	ds_read_b128 v[180:183], v200 offset:17408
	ds_read_b128 v[184:187], v200 offset:18432
	ds_read_b128 v[188:191], v200 offset:19456
	ds_read_b128 v[192:195], v200 offset:20480
	ds_read_b128 v[202:205], v200 offset:21504
	ds_read_b128 v[206:209], v200 offset:22528
	ds_read_b128 v[216:219], v200 offset:23552
	global_load_lds_dwordx4 v0, s[30:31]
	s_add_i32 m0, s49, 0x2000
	s_add_u32 s64, s30, 0x80000
	v_lshl_add_u64 v[222:223], s[30:31], 0, v[146:147]
	s_addc_u32 s65, s31, 0
	s_add_i32 s49, s51, s19
	global_load_lds_dwordx4 v146, s[30:31]
	s_mov_b32 m0, s49
	v_lshl_add_u64 v[242:243], s[36:37], 0, v[148:149]
	global_load_lds_dwordx4 v0, s[64:65]
	s_add_i32 m0, s49, 0x2000
	s_nop 0
	global_load_lds_dwordx4 v146, s[64:65]
	v_lshl_add_u64 v[240:241], s[36:37], 0, v[150:151]
	s_mov_b32 m0, s24
	s_nop 0
	global_load_lds_dwordx4 v150, s[36:37]
	s_mov_b32 m0, s56
	s_nop 0
	global_load_lds_dwordx4 v148, s[36:37]
	s_waitcnt vmcnt(8)
	s_waitcnt lgkmcnt(0)
	s_barrier
	s_setprio 1
	s_waitcnt lgkmcnt(0)
	v_mfma_f32_16x16x32_bf16 v[62:65], v[130:133], v[176:179], v[62:65]
	v_mfma_f32_16x16x32_bf16 v[58:61], v[138:141], v[176:179], v[58:61]
	v_mfma_f32_16x16x32_bf16 v[46:49], v[130:133], v[184:187], v[46:49]
	v_mfma_f32_16x16x32_bf16 v[42:45], v[138:141], v[184:187], v[42:45]
	v_mfma_f32_16x16x32_bf16 v[30:33], v[130:133], v[192:195], v[30:33]
	v_mfma_f32_16x16x32_bf16 v[26:29], v[138:141], v[192:195], v[26:29]
	v_mfma_f32_16x16x32_bf16 v[14:17], v[130:133], v[206:209], v[14:17]
	v_mfma_f32_16x16x32_bf16 v[10:13], v[138:141], v[206:209], v[10:13]
	v_mfma_f32_16x16x32_bf16 v[62:65], v[134:137], v[180:183], v[62:65]
	v_mfma_f32_16x16x32_bf16 v[58:61], v[142:145], v[180:183], v[58:61]
	v_mfma_f32_16x16x32_bf16 v[46:49], v[134:137], v[188:191], v[46:49]
	v_mfma_f32_16x16x32_bf16 v[42:45], v[142:145], v[188:191], v[42:45]
	v_mfma_f32_16x16x32_bf16 v[30:33], v[134:137], v[202:205], v[30:33]
	v_mfma_f32_16x16x32_bf16 v[26:29], v[142:145], v[202:205], v[26:29]
	v_mfma_f32_16x16x32_bf16 v[14:17], v[134:137], v[216:219], v[14:17]
	v_mfma_f32_16x16x32_bf16 v[10:13], v[142:145], v[216:219], v[10:13]
	s_setprio 0
	s_setprio 1
	v_mfma_f32_16x16x32_bf16 v[54:57], v[160:163], v[176:179], v[54:57]
	v_mfma_f32_16x16x32_bf16 v[50:53], v[168:171], v[176:179], v[50:53]
	v_mfma_f32_16x16x32_bf16 v[38:41], v[160:163], v[184:187], v[38:41]
	v_mfma_f32_16x16x32_bf16 v[34:37], v[168:171], v[184:187], v[34:37]
	v_mfma_f32_16x16x32_bf16 v[22:25], v[160:163], v[192:195], v[22:25]
	v_mfma_f32_16x16x32_bf16 v[18:21], v[168:171], v[192:195], v[18:21]
	v_mfma_f32_16x16x32_bf16 v[6:9], v[160:163], v[206:209], v[6:9]
	v_mfma_f32_16x16x32_bf16 v[2:5], v[168:171], v[206:209], v[2:5]
	v_mfma_f32_16x16x32_bf16 v[54:57], v[164:167], v[180:183], v[54:57]
	v_mfma_f32_16x16x32_bf16 v[50:53], v[172:175], v[180:183], v[50:53]
	v_mfma_f32_16x16x32_bf16 v[38:41], v[164:167], v[188:191], v[38:41]
	v_mfma_f32_16x16x32_bf16 v[34:37], v[172:175], v[188:191], v[34:37]
	v_mfma_f32_16x16x32_bf16 v[22:25], v[164:167], v[202:205], v[22:25]
	v_mfma_f32_16x16x32_bf16 v[18:21], v[172:175], v[202:205], v[18:21]
	v_mfma_f32_16x16x32_bf16 v[6:9], v[164:167], v[216:219], v[6:9]
	v_mfma_f32_16x16x32_bf16 v[2:5], v[172:175], v[216:219], v[2:5]
	s_setprio 0
	s_barrier
	s_add_i32 s49, 0, 0x18000
	s_add_i32 s51, 0, 0x1c000
	v_add_u32_e32 v142, s49, v197
	v_add_u32_e32 v172, s51, v197
	ds_read_b128 v[130:133], v142
	ds_read_b128 v[134:137], v142 offset:1024
	ds_read_b128 v[138:141], v142 offset:2048
	ds_read_b128 v[142:145], v142 offset:3072
	ds_read_b128 v[160:163], v172
	ds_read_b128 v[164:167], v172 offset:1024
	ds_read_b128 v[168:171], v172 offset:2048
	ds_read_b128 v[172:175], v172 offset:3072
	s_add_u32 s36, s36, 0x80000
	s_addc_u32 s37, s37, 0
	s_mov_b32 m0, s57
	ds_read_b128 v[176:179], v200 offset:32768
	ds_read_b128 v[180:183], v200 offset:33792
	ds_read_b128 v[184:187], v200 offset:34816
	ds_read_b128 v[188:191], v200 offset:35840
	ds_read_b128 v[192:195], v200 offset:36864
	ds_read_b128 v[202:205], v200 offset:37888
	ds_read_b128 v[206:209], v200 offset:38912
	ds_read_b128 v[216:219], v200 offset:39936
	global_load_lds_dwordx4 v150, s[36:37]
	s_mov_b32 m0, s58
	s_nop 0
	global_load_lds_dwordx4 v148, s[36:37]
	s_waitcnt vmcnt(8)
	s_waitcnt lgkmcnt(0)
	s_barrier
	s_setprio 1
	s_waitcnt lgkmcnt(0)
	v_mfma_f32_16x16x32_bf16 v[126:129], v[130:133], v[176:179], v[126:129]
	v_mfma_f32_16x16x32_bf16 v[122:125], v[138:141], v[176:179], v[122:125]
	v_mfma_f32_16x16x32_bf16 v[110:113], v[130:133], v[184:187], v[110:113]
	v_mfma_f32_16x16x32_bf16 v[106:109], v[138:141], v[184:187], v[106:109]
	v_mfma_f32_16x16x32_bf16 v[94:97], v[130:133], v[192:195], v[94:97]
	v_mfma_f32_16x16x32_bf16 v[90:93], v[138:141], v[192:195], v[90:93]
	v_mfma_f32_16x16x32_bf16 v[78:81], v[130:133], v[206:209], v[78:81]
	v_mfma_f32_16x16x32_bf16 v[74:77], v[138:141], v[206:209], v[74:77]
	v_mfma_f32_16x16x32_bf16 v[126:129], v[134:137], v[180:183], v[126:129]
	v_mfma_f32_16x16x32_bf16 v[122:125], v[142:145], v[180:183], v[122:125]
	v_mfma_f32_16x16x32_bf16 v[110:113], v[134:137], v[188:191], v[110:113]
	v_mfma_f32_16x16x32_bf16 v[106:109], v[142:145], v[188:191], v[106:109]
	v_mfma_f32_16x16x32_bf16 v[94:97], v[134:137], v[202:205], v[94:97]
	v_mfma_f32_16x16x32_bf16 v[90:93], v[142:145], v[202:205], v[90:93]
	v_mfma_f32_16x16x32_bf16 v[78:81], v[134:137], v[216:219], v[78:81]
	v_mfma_f32_16x16x32_bf16 v[74:77], v[142:145], v[216:219], v[74:77]
	s_setprio 0
	s_setprio 1
	v_mfma_f32_16x16x32_bf16 v[118:121], v[160:163], v[176:179], v[118:121]
	v_mfma_f32_16x16x32_bf16 v[114:117], v[168:171], v[176:179], v[114:117]
	v_mfma_f32_16x16x32_bf16 v[102:105], v[160:163], v[184:187], v[102:105]
	v_mfma_f32_16x16x32_bf16 v[98:101], v[168:171], v[184:187], v[98:101]
	v_mfma_f32_16x16x32_bf16 v[86:89], v[160:163], v[192:195], v[86:89]
	v_mfma_f32_16x16x32_bf16 v[82:85], v[168:171], v[192:195], v[82:85]
	v_mfma_f32_16x16x32_bf16 v[70:73], v[160:163], v[206:209], v[70:73]
	v_mfma_f32_16x16x32_bf16 v[66:69], v[168:171], v[206:209], v[66:69]
	v_mfma_f32_16x16x32_bf16 v[118:121], v[164:167], v[180:183], v[118:121]
	v_mfma_f32_16x16x32_bf16 v[114:117], v[172:175], v[180:183], v[114:117]
	v_mfma_f32_16x16x32_bf16 v[102:105], v[164:167], v[188:191], v[102:105]
	v_mfma_f32_16x16x32_bf16 v[98:101], v[172:175], v[188:191], v[98:101]
	v_mfma_f32_16x16x32_bf16 v[86:89], v[164:167], v[202:205], v[86:89]
	v_mfma_f32_16x16x32_bf16 v[82:85], v[172:175], v[202:205], v[82:85]
	v_mfma_f32_16x16x32_bf16 v[70:73], v[164:167], v[216:219], v[70:73]
	v_mfma_f32_16x16x32_bf16 v[66:69], v[172:175], v[216:219], v[66:69]
	s_setprio 0
	s_barrier
	s_add_i32 s36, s49, s19
	v_lshl_add_u64 v[220:221], v[220:221], 0, s[22:23]
	s_mov_b32 m0, s36
	ds_read_b128 v[176:179], v200 offset:49152
	ds_read_b128 v[180:183], v200 offset:50176
	ds_read_b128 v[184:187], v200 offset:51200
	ds_read_b128 v[188:191], v200 offset:52224
	ds_read_b128 v[192:195], v200 offset:53248
	ds_read_b128 v[202:205], v200 offset:54272
	ds_read_b128 v[206:209], v200 offset:55296
	ds_read_b128 v[216:219], v200 offset:56320
	global_load_lds_dwordx4 v[220:221], off
	s_add_i32 m0, s36, 0x2000
	s_add_u32 s30, s30, 0x80080
	v_lshl_add_u64 v[220:221], v[222:223], 0, s[22:23]
	s_addc_u32 s31, s31, 0
	s_add_i32 s36, s51, s19
	global_load_lds_dwordx4 v[220:221], off
	s_mov_b32 m0, s36
	s_nop 0
	global_load_lds_dwordx4 v0, s[30:31]
	s_add_i32 m0, s36, 0x2000
	s_nop 0
	global_load_lds_dwordx4 v146, s[30:31]
	v_lshl_add_u64 v[220:221], v[240:241], 0, s[22:23]
	s_mov_b32 m0, s59
	s_nop 0
	global_load_lds_dwordx4 v[220:221], off
	v_lshl_add_u64 v[220:221], v[242:243], 0, s[22:23]
	s_mov_b32 m0, s60
	s_nop 0
	global_load_lds_dwordx4 v[220:221], off
	s_waitcnt vmcnt(8)
	s_waitcnt lgkmcnt(0)
	s_barrier
	s_setprio 1
	s_waitcnt lgkmcnt(0)
	v_mfma_f32_16x16x32_bf16 v[62:65], v[130:133], v[176:179], v[62:65]
	v_mfma_f32_16x16x32_bf16 v[58:61], v[138:141], v[176:179], v[58:61]
	v_mfma_f32_16x16x32_bf16 v[46:49], v[130:133], v[184:187], v[46:49]
	v_mfma_f32_16x16x32_bf16 v[42:45], v[138:141], v[184:187], v[42:45]
	v_mfma_f32_16x16x32_bf16 v[30:33], v[130:133], v[192:195], v[30:33]
	v_mfma_f32_16x16x32_bf16 v[26:29], v[138:141], v[192:195], v[26:29]
	v_mfma_f32_16x16x32_bf16 v[14:17], v[130:133], v[206:209], v[14:17]
	v_mfma_f32_16x16x32_bf16 v[10:13], v[138:141], v[206:209], v[10:13]
	v_mfma_f32_16x16x32_bf16 v[62:65], v[134:137], v[180:183], v[62:65]
	v_mfma_f32_16x16x32_bf16 v[58:61], v[142:145], v[180:183], v[58:61]
	v_mfma_f32_16x16x32_bf16 v[46:49], v[134:137], v[188:191], v[46:49]
	v_mfma_f32_16x16x32_bf16 v[42:45], v[142:145], v[188:191], v[42:45]
	v_mfma_f32_16x16x32_bf16 v[30:33], v[134:137], v[202:205], v[30:33]
	v_mfma_f32_16x16x32_bf16 v[26:29], v[142:145], v[202:205], v[26:29]
	v_mfma_f32_16x16x32_bf16 v[14:17], v[134:137], v[216:219], v[14:17]
	v_mfma_f32_16x16x32_bf16 v[10:13], v[142:145], v[216:219], v[10:13]
	s_setprio 0
	s_setprio 1
	v_mfma_f32_16x16x32_bf16 v[54:57], v[160:163], v[176:179], v[54:57]
	v_mfma_f32_16x16x32_bf16 v[50:53], v[168:171], v[176:179], v[50:53]
	v_mfma_f32_16x16x32_bf16 v[38:41], v[160:163], v[184:187], v[38:41]
	v_mfma_f32_16x16x32_bf16 v[34:37], v[168:171], v[184:187], v[34:37]
	v_mfma_f32_16x16x32_bf16 v[22:25], v[160:163], v[192:195], v[22:25]
	v_mfma_f32_16x16x32_bf16 v[18:21], v[168:171], v[192:195], v[18:21]
	v_mfma_f32_16x16x32_bf16 v[6:9], v[160:163], v[206:209], v[6:9]
	v_mfma_f32_16x16x32_bf16 v[2:5], v[168:171], v[206:209], v[2:5]
	v_mfma_f32_16x16x32_bf16 v[54:57], v[164:167], v[180:183], v[54:57]
	v_mfma_f32_16x16x32_bf16 v[50:53], v[172:175], v[180:183], v[50:53]
	v_mfma_f32_16x16x32_bf16 v[38:41], v[164:167], v[188:191], v[38:41]
	v_mfma_f32_16x16x32_bf16 v[34:37], v[172:175], v[188:191], v[34:37]
	v_mfma_f32_16x16x32_bf16 v[22:25], v[164:167], v[202:205], v[22:25]
	v_mfma_f32_16x16x32_bf16 v[18:21], v[172:175], v[202:205], v[18:21]
	v_mfma_f32_16x16x32_bf16 v[6:9], v[164:167], v[216:219], v[6:9]
	v_mfma_f32_16x16x32_bf16 v[2:5], v[172:175], v[216:219], v[2:5]
	s_setprio 0
	s_barrier
	s_add_i32 s47, s47, 2
	s_add_u32 s2, s2, 0x100
	s_addc_u32 s3, s3, 0
	s_add_u32 s45, s45, 0x100
	s_addc_u32 s46, s46, 0
	s_cmp_gt_u32 s47, 29
	s_cbranch_scc0 .LBB0_411
	s_and_b64 vcc, exec, s[6:7]
	s_cbranch_vccz .LBB0_414
	s_barrier

.LBB0_554:
	s_add_u32 s30, s2, 0xfff80080
	s_addc_u32 s31, s3, -1
	s_add_i32 s59, 0, 0x10000
	s_cmp_eq_u32 s58, 28
	s_cselect_b32 s41, s37, s31
	s_cselect_b32 s40, s54, s30
	s_cselect_b32 s31, s9, s57
	s_cselect_b32 s30, s55, s56
	s_add_i32 s62, 0, 0x14000
	v_add_u32_e32 v152, s59, v164
	v_add_u32_e32 v160, s62, v164
	ds_read_b128 v[140:143], v152
	ds_read_b128 v[144:147], v152 offset:1024
	ds_read_b128 v[148:151], v152 offset:2048
	ds_read_b128 v[152:155], v152 offset:3072
	ds_read_b128 v[156:159], v160
	ds_read_b128 v[168:171], v160 offset:1024
	ds_read_b128 v[172:175], v160 offset:2048
	ds_read_b128 v[176:179], v160 offset:3072
	s_add_i32 m0, s24, 0xc000
	ds_read_b128 v[180:183], v167
	ds_read_b128 v[184:187], v167 offset:1024
	ds_read_b128 v[188:191], v167 offset:2048
	ds_read_b128 v[192:195], v167 offset:3072
	ds_read_b128 v[196:199], v167 offset:4096
	ds_read_b128 v[200:203], v167 offset:5120
	ds_read_b128 v[204:207], v167 offset:6144
	ds_read_b128 v[216:219], v167 offset:7168
	global_load_lds_dwordx4 v136, s[2:3]
	s_add_i32 m0, s24, 0xe000
	s_nop 0
	global_load_lds_dwordx4 v138, s[2:3]
	s_waitcnt vmcnt(8)
	s_waitcnt lgkmcnt(0)
	s_barrier
	s_setprio 1
	s_waitcnt lgkmcnt(0)
	v_mfma_f32_16x16x32_bf16 v[126:129], v[140:143], v[180:183], v[126:129]
	v_mfma_f32_16x16x32_bf16 v[122:125], v[148:151], v[180:183], v[122:125]
	v_mfma_f32_16x16x32_bf16 v[110:113], v[140:143], v[188:191], v[110:113]
	v_mfma_f32_16x16x32_bf16 v[106:109], v[148:151], v[188:191], v[106:109]
	v_mfma_f32_16x16x32_bf16 v[94:97], v[140:143], v[196:199], v[94:97]
	v_mfma_f32_16x16x32_bf16 v[90:93], v[148:151], v[196:199], v[90:93]
	v_mfma_f32_16x16x32_bf16 v[78:81], v[140:143], v[204:207], v[78:81]
	v_mfma_f32_16x16x32_bf16 v[74:77], v[148:151], v[204:207], v[74:77]
	v_mfma_f32_16x16x32_bf16 v[126:129], v[144:147], v[184:187], v[126:129]
	v_mfma_f32_16x16x32_bf16 v[122:125], v[152:155], v[184:187], v[122:125]
	v_mfma_f32_16x16x32_bf16 v[110:113], v[144:147], v[192:195], v[110:113]
	v_mfma_f32_16x16x32_bf16 v[106:109], v[152:155], v[192:195], v[106:109]
	v_mfma_f32_16x16x32_bf16 v[94:97], v[144:147], v[200:203], v[94:97]
	v_mfma_f32_16x16x32_bf16 v[90:93], v[152:155], v[200:203], v[90:93]
	v_mfma_f32_16x16x32_bf16 v[78:81], v[144:147], v[216:219], v[78:81]
	v_mfma_f32_16x16x32_bf16 v[74:77], v[152:155], v[216:219], v[74:77]
	s_setprio 0
	s_setprio 1
	v_mfma_f32_16x16x32_bf16 v[118:121], v[156:159], v[180:183], v[118:121]
	v_mfma_f32_16x16x32_bf16 v[114:117], v[172:175], v[180:183], v[114:117]
	v_mfma_f32_16x16x32_bf16 v[102:105], v[156:159], v[188:191], v[102:105]
	v_mfma_f32_16x16x32_bf16 v[98:101], v[172:175], v[188:191], v[98:101]
	v_mfma_f32_16x16x32_bf16 v[86:89], v[156:159], v[196:199], v[86:89]
	v_mfma_f32_16x16x32_bf16 v[82:85], v[172:175], v[196:199], v[82:85]
	v_mfma_f32_16x16x32_bf16 v[70:73], v[156:159], v[204:207], v[70:73]
	v_mfma_f32_16x16x32_bf16 v[66:69], v[172:175], v[204:207], v[66:69]
	v_mfma_f32_16x16x32_bf16 v[118:121], v[168:171], v[184:187], v[118:121]
	v_mfma_f32_16x16x32_bf16 v[114:117], v[176:179], v[184:187], v[114:117]
	v_mfma_f32_16x16x32_bf16 v[102:105], v[168:171], v[192:195], v[102:105]
	v_mfma_f32_16x16x32_bf16 v[98:101], v[176:179], v[192:195], v[98:101]
	v_mfma_f32_16x16x32_bf16 v[86:89], v[168:171], v[200:203], v[86:89]
	v_mfma_f32_16x16x32_bf16 v[82:85], v[176:179], v[200:203], v[82:85]
	v_mfma_f32_16x16x32_bf16 v[70:73], v[168:171], v[216:219], v[70:73]
	v_mfma_f32_16x16x32_bf16 v[66:69], v[176:179], v[216:219], v[66:69]
	s_setprio 0
	s_barrier
	s_add_i32 s59, s59, s19
	v_lshl_add_u64 v[160:161], s[30:31], 0, v[0:1]
	s_mov_b32 m0, s59
	ds_read_b128 v[180:183], v167 offset:16384
	ds_read_b128 v[184:187], v167 offset:17408
	ds_read_b128 v[188:191], v167 offset:18432
	ds_read_b128 v[192:195], v167 offset:19456
	ds_read_b128 v[196:199], v167 offset:20480
	ds_read_b128 v[200:203], v167 offset:21504
	ds_read_b128 v[204:207], v167 offset:22528
	ds_read_b128 v[216:219], v167 offset:23552
	global_load_lds_dwordx4 v0, s[30:31]
	s_add_i32 m0, s59, 0x2000
	s_add_u32 s60, s30, 0x80000
	v_lshl_add_u64 v[208:209], s[30:31], 0, v[130:131]
	s_addc_u32 s61, s31, 0
	s_add_i32 s59, s62, s19
	global_load_lds_dwordx4 v130, s[30:31]
	s_mov_b32 m0, s59
	v_lshl_add_u64 v[222:223], s[40:41], 0, v[132:133]
	global_load_lds_dwordx4 v0, s[60:61]
	s_add_i32 m0, s59, 0x2000
	s_nop 0
	global_load_lds_dwordx4 v130, s[60:61]
	v_lshl_add_u64 v[220:221], s[40:41], 0, v[134:135]
	s_mov_b32 m0, s24
	s_nop 0
	global_load_lds_dwordx4 v134, s[40:41]
	s_mov_b32 m0, s46
	s_nop 0
	global_load_lds_dwordx4 v132, s[40:41]
	s_waitcnt vmcnt(8)
	s_waitcnt lgkmcnt(0)
	s_barrier
	s_setprio 1
	s_waitcnt lgkmcnt(0)
	v_mfma_f32_16x16x32_bf16 v[62:65], v[140:143], v[180:183], v[62:65]
	v_mfma_f32_16x16x32_bf16 v[58:61], v[148:151], v[180:183], v[58:61]
	v_mfma_f32_16x16x32_bf16 v[46:49], v[140:143], v[188:191], v[46:49]
	v_mfma_f32_16x16x32_bf16 v[42:45], v[148:151], v[188:191], v[42:45]
	v_mfma_f32_16x16x32_bf16 v[30:33], v[140:143], v[196:199], v[30:33]
	v_mfma_f32_16x16x32_bf16 v[26:29], v[148:151], v[196:199], v[26:29]
	v_mfma_f32_16x16x32_bf16 v[14:17], v[140:143], v[204:207], v[14:17]
	v_mfma_f32_16x16x32_bf16 v[10:13], v[148:151], v[204:207], v[10:13]
	v_mfma_f32_16x16x32_bf16 v[62:65], v[144:147], v[184:187], v[62:65]
	v_mfma_f32_16x16x32_bf16 v[58:61], v[152:155], v[184:187], v[58:61]
	v_mfma_f32_16x16x32_bf16 v[46:49], v[144:147], v[192:195], v[46:49]
	v_mfma_f32_16x16x32_bf16 v[42:45], v[152:155], v[192:195], v[42:45]
	v_mfma_f32_16x16x32_bf16 v[30:33], v[144:147], v[200:203], v[30:33]
	v_mfma_f32_16x16x32_bf16 v[26:29], v[152:155], v[200:203], v[26:29]
	v_mfma_f32_16x16x32_bf16 v[14:17], v[144:147], v[216:219], v[14:17]
	v_mfma_f32_16x16x32_bf16 v[10:13], v[152:155], v[216:219], v[10:13]
	s_setprio 0
	s_setprio 1
	v_mfma_f32_16x16x32_bf16 v[54:57], v[156:159], v[180:183], v[54:57]
	v_mfma_f32_16x16x32_bf16 v[50:53], v[172:175], v[180:183], v[50:53]
	v_mfma_f32_16x16x32_bf16 v[38:41], v[156:159], v[188:191], v[38:41]
	v_mfma_f32_16x16x32_bf16 v[34:37], v[172:175], v[188:191], v[34:37]
	v_mfma_f32_16x16x32_bf16 v[22:25], v[156:159], v[196:199], v[22:25]
	v_mfma_f32_16x16x32_bf16 v[18:21], v[172:175], v[196:199], v[18:21]
	v_mfma_f32_16x16x32_bf16 v[6:9], v[156:159], v[204:207], v[6:9]
	v_mfma_f32_16x16x32_bf16 v[2:5], v[172:175], v[204:207], v[2:5]
	v_mfma_f32_16x16x32_bf16 v[54:57], v[168:171], v[184:187], v[54:57]
	v_mfma_f32_16x16x32_bf16 v[50:53], v[176:179], v[184:187], v[50:53]
	v_mfma_f32_16x16x32_bf16 v[38:41], v[168:171], v[192:195], v[38:41]
	v_mfma_f32_16x16x32_bf16 v[34:37], v[176:179], v[192:195], v[34:37]
	v_mfma_f32_16x16x32_bf16 v[22:25], v[168:171], v[200:203], v[22:25]
	v_mfma_f32_16x16x32_bf16 v[18:21], v[176:179], v[200:203], v[18:21]
	v_mfma_f32_16x16x32_bf16 v[6:9], v[168:171], v[216:219], v[6:9]
	v_mfma_f32_16x16x32_bf16 v[2:5], v[176:179], v[216:219], v[2:5]
	s_setprio 0
	s_barrier
	s_add_i32 s59, 0, 0x18000
	s_add_i32 s60, 0, 0x1c000
	v_add_u32_e32 v152, s59, v164
	v_add_u32_e32 v176, s60, v164
	ds_read_b128 v[140:143], v152
	ds_read_b128 v[144:147], v152 offset:1024
	ds_read_b128 v[148:151], v152 offset:2048
	ds_read_b128 v[152:155], v152 offset:3072
	ds_read_b128 v[156:159], v176
	ds_read_b128 v[168:171], v176 offset:1024
	ds_read_b128 v[172:175], v176 offset:2048
	ds_read_b128 v[176:179], v176 offset:3072
	s_add_u32 s40, s40, 0x80000
	s_addc_u32 s41, s41, 0
	s_mov_b32 m0, s47
	ds_read_b128 v[180:183], v167 offset:32768
	ds_read_b128 v[184:187], v167 offset:33792
	ds_read_b128 v[188:191], v167 offset:34816
	ds_read_b128 v[192:195], v167 offset:35840
	ds_read_b128 v[196:199], v167 offset:36864
	ds_read_b128 v[200:203], v167 offset:37888
	ds_read_b128 v[204:207], v167 offset:38912
	ds_read_b128 v[216:219], v167 offset:39936
	global_load_lds_dwordx4 v134, s[40:41]
	s_mov_b32 m0, s48
	s_nop 0
	global_load_lds_dwordx4 v132, s[40:41]
	s_waitcnt vmcnt(8)
	s_waitcnt lgkmcnt(0)
	s_barrier
	s_setprio 1
	s_waitcnt lgkmcnt(0)
	v_mfma_f32_16x16x32_bf16 v[126:129], v[140:143], v[180:183], v[126:129]
	v_mfma_f32_16x16x32_bf16 v[122:125], v[148:151], v[180:183], v[122:125]
	v_mfma_f32_16x16x32_bf16 v[110:113], v[140:143], v[188:191], v[110:113]
	v_mfma_f32_16x16x32_bf16 v[106:109], v[148:151], v[188:191], v[106:109]
	v_mfma_f32_16x16x32_bf16 v[94:97], v[140:143], v[196:199], v[94:97]
	v_mfma_f32_16x16x32_bf16 v[90:93], v[148:151], v[196:199], v[90:93]
	v_mfma_f32_16x16x32_bf16 v[78:81], v[140:143], v[204:207], v[78:81]
	v_mfma_f32_16x16x32_bf16 v[74:77], v[148:151], v[204:207], v[74:77]
	v_mfma_f32_16x16x32_bf16 v[126:129], v[144:147], v[184:187], v[126:129]
	v_mfma_f32_16x16x32_bf16 v[122:125], v[152:155], v[184:187], v[122:125]
	v_mfma_f32_16x16x32_bf16 v[110:113], v[144:147], v[192:195], v[110:113]
	v_mfma_f32_16x16x32_bf16 v[106:109], v[152:155], v[192:195], v[106:109]
	v_mfma_f32_16x16x32_bf16 v[94:97], v[144:147], v[200:203], v[94:97]
	v_mfma_f32_16x16x32_bf16 v[90:93], v[152:155], v[200:203], v[90:93]
	v_mfma_f32_16x16x32_bf16 v[78:81], v[144:147], v[216:219], v[78:81]
	v_mfma_f32_16x16x32_bf16 v[74:77], v[152:155], v[216:219], v[74:77]
	s_setprio 0
	s_setprio 1
	v_mfma_f32_16x16x32_bf16 v[118:121], v[156:159], v[180:183], v[118:121]
	v_mfma_f32_16x16x32_bf16 v[114:117], v[172:175], v[180:183], v[114:117]
	v_mfma_f32_16x16x32_bf16 v[102:105], v[156:159], v[188:191], v[102:105]
	v_mfma_f32_16x16x32_bf16 v[98:101], v[172:175], v[188:191], v[98:101]
	v_mfma_f32_16x16x32_bf16 v[86:89], v[156:159], v[196:199], v[86:89]
	v_mfma_f32_16x16x32_bf16 v[82:85], v[172:175], v[196:199], v[82:85]
	v_mfma_f32_16x16x32_bf16 v[70:73], v[156:159], v[204:207], v[70:73]
	v_mfma_f32_16x16x32_bf16 v[66:69], v[172:175], v[204:207], v[66:69]
	v_mfma_f32_16x16x32_bf16 v[118:121], v[168:171], v[184:187], v[118:121]
	v_mfma_f32_16x16x32_bf16 v[114:117], v[176:179], v[184:187], v[114:117]
	v_mfma_f32_16x16x32_bf16 v[102:105], v[168:171], v[192:195], v[102:105]
	v_mfma_f32_16x16x32_bf16 v[98:101], v[176:179], v[192:195], v[98:101]
	v_mfma_f32_16x16x32_bf16 v[86:89], v[168:171], v[200:203], v[86:89]
	v_mfma_f32_16x16x32_bf16 v[82:85], v[176:179], v[200:203], v[82:85]
	v_mfma_f32_16x16x32_bf16 v[70:73], v[168:171], v[216:219], v[70:73]
	v_mfma_f32_16x16x32_bf16 v[66:69], v[176:179], v[216:219], v[66:69]
	s_setprio 0
	s_barrier
	s_add_i32 s40, s59, s19
	v_lshl_add_u64 v[160:161], v[160:161], 0, s[22:23]
	s_mov_b32 m0, s40
	ds_read_b128 v[180:183], v167 offset:49152
	ds_read_b128 v[184:187], v167 offset:50176
	ds_read_b128 v[188:191], v167 offset:51200
	ds_read_b128 v[192:195], v167 offset:52224
	ds_read_b128 v[196:199], v167 offset:53248
	ds_read_b128 v[200:203], v167 offset:54272
	ds_read_b128 v[204:207], v167 offset:55296
	ds_read_b128 v[216:219], v167 offset:56320
	global_load_lds_dwordx4 v[160:161], off
	s_add_i32 m0, s40, 0x2000
	s_add_u32 s30, s30, 0x80080
	v_lshl_add_u64 v[160:161], v[208:209], 0, s[22:23]
	s_addc_u32 s31, s31, 0
	s_add_i32 s40, s60, s19
	global_load_lds_dwordx4 v[160:161], off
	s_mov_b32 m0, s40
	s_nop 0
	global_load_lds_dwordx4 v0, s[30:31]
	s_add_i32 m0, s40, 0x2000
	s_nop 0
	global_load_lds_dwordx4 v130, s[30:31]
	v_lshl_add_u64 v[160:161], v[220:221], 0, s[22:23]
	s_mov_b32 m0, s49
	s_nop 0
	global_load_lds_dwordx4 v[160:161], off
	v_lshl_add_u64 v[160:161], v[222:223], 0, s[22:23]
	s_mov_b32 m0, s50
	s_nop 0
	global_load_lds_dwordx4 v[160:161], off
	s_waitcnt vmcnt(8)
	s_waitcnt lgkmcnt(0)
	s_barrier
	s_setprio 1
	s_waitcnt lgkmcnt(0)
	v_mfma_f32_16x16x32_bf16 v[62:65], v[140:143], v[180:183], v[62:65]
	v_mfma_f32_16x16x32_bf16 v[58:61], v[148:151], v[180:183], v[58:61]
	v_mfma_f32_16x16x32_bf16 v[46:49], v[140:143], v[188:191], v[46:49]
	v_mfma_f32_16x16x32_bf16 v[42:45], v[148:151], v[188:191], v[42:45]
	v_mfma_f32_16x16x32_bf16 v[30:33], v[140:143], v[196:199], v[30:33]
	v_mfma_f32_16x16x32_bf16 v[26:29], v[148:151], v[196:199], v[26:29]
	v_mfma_f32_16x16x32_bf16 v[14:17], v[140:143], v[204:207], v[14:17]
	v_mfma_f32_16x16x32_bf16 v[10:13], v[148:151], v[204:207], v[10:13]
	v_mfma_f32_16x16x32_bf16 v[62:65], v[144:147], v[184:187], v[62:65]
	v_mfma_f32_16x16x32_bf16 v[58:61], v[152:155], v[184:187], v[58:61]
	v_mfma_f32_16x16x32_bf16 v[46:49], v[144:147], v[192:195], v[46:49]
	v_mfma_f32_16x16x32_bf16 v[42:45], v[152:155], v[192:195], v[42:45]
	v_mfma_f32_16x16x32_bf16 v[30:33], v[144:147], v[200:203], v[30:33]
	v_mfma_f32_16x16x32_bf16 v[26:29], v[152:155], v[200:203], v[26:29]
	v_mfma_f32_16x16x32_bf16 v[14:17], v[144:147], v[216:219], v[14:17]
	v_mfma_f32_16x16x32_bf16 v[10:13], v[152:155], v[216:219], v[10:13]
	s_setprio 0
	s_setprio 1
	v_mfma_f32_16x16x32_bf16 v[54:57], v[156:159], v[180:183], v[54:57]
	v_mfma_f32_16x16x32_bf16 v[50:53], v[172:175], v[180:183], v[50:53]
	v_mfma_f32_16x16x32_bf16 v[38:41], v[156:159], v[188:191], v[38:41]
	v_mfma_f32_16x16x32_bf16 v[34:37], v[172:175], v[188:191], v[34:37]
	v_mfma_f32_16x16x32_bf16 v[22:25], v[156:159], v[196:199], v[22:25]
	v_mfma_f32_16x16x32_bf16 v[18:21], v[172:175], v[196:199], v[18:21]
	v_mfma_f32_16x16x32_bf16 v[6:9], v[156:159], v[204:207], v[6:9]
	v_mfma_f32_16x16x32_bf16 v[2:5], v[172:175], v[204:207], v[2:5]
	v_mfma_f32_16x16x32_bf16 v[54:57], v[168:171], v[184:187], v[54:57]
	v_mfma_f32_16x16x32_bf16 v[50:53], v[176:179], v[184:187], v[50:53]
	v_mfma_f32_16x16x32_bf16 v[38:41], v[168:171], v[192:195], v[38:41]
	v_mfma_f32_16x16x32_bf16 v[34:37], v[176:179], v[192:195], v[34:37]
	v_mfma_f32_16x16x32_bf16 v[22:25], v[168:171], v[200:203], v[22:25]
	v_mfma_f32_16x16x32_bf16 v[18:21], v[176:179], v[200:203], v[18:21]
	v_mfma_f32_16x16x32_bf16 v[6:9], v[168:171], v[216:219], v[6:9]
	v_mfma_f32_16x16x32_bf16 v[2:5], v[176:179], v[216:219], v[2:5]
	s_setprio 0
	s_barrier
	s_add_i32 s58, s58, 2
	s_add_u32 s2, s2, 0x100
	s_addc_u32 s3, s3, 0
	s_add_u32 s56, s56, 0x100
	s_addc_u32 s57, s57, 0
	s_cmp_gt_u32 s58, 29
	s_cbranch_scc0 .LBB0_554
	s_and_b64 vcc, exec, s[6:7]
	s_cbranch_vccz .LBB0_557
	s_barrier

.LBB0_1493:
	s_add_i32 s63, s30, 2
	s_add_u32 s31, s2, 0xfff80080
	s_addc_u32 s40, s3, -1
	s_add_i32 s64, 0, 0x10000
	s_cmp_eq_u32 s60, s30
	s_cselect_b32 s41, s37, s40
	s_cselect_b32 s40, s43, s31
	v_add_u32_e32 v0, s64, v185
	s_cselect_b32 s31, s9, s62
	s_cselect_b32 s30, s59, s61
	s_add_i32 s66, 0, 0x14000
	ds_read_b128 v[134:137], v0
	ds_read_b128 v[138:141], v0 offset:1024
	ds_read_b128 v[142:145], v0 offset:2048
	ds_read_b128 v[146:149], v0 offset:3072
	v_add_u32_e32 v0, s66, v185
	ds_read_b128 v[150:153], v0
	ds_read_b128 v[154:157], v0 offset:1024
	ds_read_b128 v[158:161], v0 offset:2048
	ds_read_b128 v[176:179], v0 offset:3072
	s_add_i32 m0, s48, 0xc000
	ds_read_b128 v[180:183], v187
	ds_read_b128 v[190:193], v187 offset:1024
	ds_read_b128 v[194:197], v187 offset:2048
	ds_read_b128 v[198:201], v187 offset:3072
	ds_read_b128 v[202:205], v187 offset:4096
	ds_read_b128 v[206:209], v187 offset:5120
	ds_read_b128 v[216:219], v187 offset:6144
	ds_read_b128 v[220:223], v187 offset:7168
	global_load_lds_dwordx4 v172, s[2:3]
	s_add_i32 m0, s48, 0xe000
	s_nop 0
	global_load_lds_dwordx4 v174, s[2:3]
	s_waitcnt vmcnt(8)
	s_waitcnt lgkmcnt(0)
	s_barrier
	s_setprio 1
	s_waitcnt lgkmcnt(0)
	v_mfma_f32_16x16x32_bf16 v[128:131], v[134:137], v[180:183], v[128:131]
	v_mfma_f32_16x16x32_bf16 v[124:127], v[142:145], v[180:183], v[124:127]
	v_mfma_f32_16x16x32_bf16 v[120:123], v[134:137], v[194:197], v[120:123]
	v_mfma_f32_16x16x32_bf16 v[116:119], v[142:145], v[194:197], v[116:119]
	v_mfma_f32_16x16x32_bf16 v[112:115], v[134:137], v[202:205], v[112:115]
	v_mfma_f32_16x16x32_bf16 v[108:111], v[142:145], v[202:205], v[108:111]
	v_mfma_f32_16x16x32_bf16 v[104:107], v[134:137], v[216:219], v[104:107]
	v_mfma_f32_16x16x32_bf16 v[100:103], v[142:145], v[216:219], v[100:103]
	v_mfma_f32_16x16x32_bf16 v[128:131], v[138:141], v[190:193], v[128:131]
	v_mfma_f32_16x16x32_bf16 v[124:127], v[146:149], v[190:193], v[124:127]
	v_mfma_f32_16x16x32_bf16 v[120:123], v[138:141], v[198:201], v[120:123]
	v_mfma_f32_16x16x32_bf16 v[116:119], v[146:149], v[198:201], v[116:119]
	v_mfma_f32_16x16x32_bf16 v[112:115], v[138:141], v[206:209], v[112:115]
	v_mfma_f32_16x16x32_bf16 v[108:111], v[146:149], v[206:209], v[108:111]
	v_mfma_f32_16x16x32_bf16 v[104:107], v[138:141], v[220:223], v[104:107]
	v_mfma_f32_16x16x32_bf16 v[100:103], v[146:149], v[220:223], v[100:103]
	s_setprio 0
	s_setprio 1
	v_mfma_f32_16x16x32_bf16 v[96:99], v[150:153], v[180:183], v[96:99]
	v_mfma_f32_16x16x32_bf16 v[92:95], v[158:161], v[180:183], v[92:95]
	v_mfma_f32_16x16x32_bf16 v[88:91], v[150:153], v[194:197], v[88:91]
	v_mfma_f32_16x16x32_bf16 v[84:87], v[158:161], v[194:197], v[84:87]
	v_mfma_f32_16x16x32_bf16 v[80:83], v[150:153], v[202:205], v[80:83]
	v_mfma_f32_16x16x32_bf16 v[76:79], v[158:161], v[202:205], v[76:79]
	v_mfma_f32_16x16x32_bf16 v[72:75], v[150:153], v[216:219], v[72:75]
	v_mfma_f32_16x16x32_bf16 v[68:71], v[158:161], v[216:219], v[68:71]
	v_mfma_f32_16x16x32_bf16 v[96:99], v[154:157], v[190:193], v[96:99]
	v_mfma_f32_16x16x32_bf16 v[92:95], v[176:179], v[190:193], v[92:95]
	v_mfma_f32_16x16x32_bf16 v[88:91], v[154:157], v[198:201], v[88:91]
	v_mfma_f32_16x16x32_bf16 v[84:87], v[176:179], v[198:201], v[84:87]
	v_mfma_f32_16x16x32_bf16 v[80:83], v[154:157], v[206:209], v[80:83]
	v_mfma_f32_16x16x32_bf16 v[76:79], v[176:179], v[206:209], v[76:79]
	v_mfma_f32_16x16x32_bf16 v[72:75], v[154:157], v[220:223], v[72:75]
	v_mfma_f32_16x16x32_bf16 v[68:71], v[176:179], v[220:223], v[68:71]
	s_setprio 0
	s_barrier
	s_add_i32 s64, s64, s19
	v_lshl_add_u64 v[162:163], s[30:31], 0, v[168:169]
	s_mov_b32 m0, s64
	ds_read_b128 v[180:183], v187 offset:16384
	ds_read_b128 v[190:193], v187 offset:17408
	ds_read_b128 v[194:197], v187 offset:18432
	ds_read_b128 v[198:201], v187 offset:19456
	ds_read_b128 v[202:205], v187 offset:20480
	ds_read_b128 v[206:209], v187 offset:21504
	ds_read_b128 v[216:219], v187 offset:22528
	ds_read_b128 v[220:223], v187 offset:23552
	global_load_lds_dwordx4 v168, s[30:31]
	s_add_i32 m0, s64, 0x2000
	s_add_u32 s64, s30, 0x80000
	v_lshl_add_u64 v[240:241], s[30:31], 0, v[164:165]
	s_addc_u32 s65, s31, 0
	s_add_i32 s66, s66, s19
	global_load_lds_dwordx4 v164, s[30:31]
	s_mov_b32 m0, s66
	v_lshl_add_u64 v[242:243], s[40:41], 0, v[170:171]
	global_load_lds_dwordx4 v168, s[64:65]
	s_add_i32 m0, s66, 0x2000
	v_lshl_add_u64 v[244:245], s[40:41], 0, v[166:167]
	global_load_lds_dwordx4 v164, s[64:65]
	s_mov_b32 m0, s48
	s_nop 0
	global_load_lds_dwordx4 v170, s[40:41]
	s_mov_b32 m0, s49
	s_nop 0
	global_load_lds_dwordx4 v166, s[40:41]
	s_waitcnt vmcnt(8)
	s_waitcnt lgkmcnt(0)
	s_barrier
	s_setprio 1
	s_waitcnt lgkmcnt(0)
	v_mfma_f32_16x16x32_bf16 v[64:67], v[134:137], v[180:183], v[64:67]
	v_mfma_f32_16x16x32_bf16 v[60:63], v[142:145], v[180:183], v[60:63]
	v_mfma_f32_16x16x32_bf16 v[56:59], v[134:137], v[194:197], v[56:59]
	v_mfma_f32_16x16x32_bf16 v[52:55], v[142:145], v[194:197], v[52:55]
	v_mfma_f32_16x16x32_bf16 v[48:51], v[134:137], v[202:205], v[48:51]
	v_mfma_f32_16x16x32_bf16 v[44:47], v[142:145], v[202:205], v[44:47]
	v_mfma_f32_16x16x32_bf16 v[40:43], v[134:137], v[216:219], v[40:43]
	v_mfma_f32_16x16x32_bf16 v[36:39], v[142:145], v[216:219], v[36:39]
	v_mfma_f32_16x16x32_bf16 v[64:67], v[138:141], v[190:193], v[64:67]
	v_mfma_f32_16x16x32_bf16 v[60:63], v[146:149], v[190:193], v[60:63]
	v_mfma_f32_16x16x32_bf16 v[56:59], v[138:141], v[198:201], v[56:59]
	v_mfma_f32_16x16x32_bf16 v[52:55], v[146:149], v[198:201], v[52:55]
	v_mfma_f32_16x16x32_bf16 v[48:51], v[138:141], v[206:209], v[48:51]
	v_mfma_f32_16x16x32_bf16 v[44:47], v[146:149], v[206:209], v[44:47]
	v_mfma_f32_16x16x32_bf16 v[40:43], v[138:141], v[220:223], v[40:43]
	v_mfma_f32_16x16x32_bf16 v[36:39], v[146:149], v[220:223], v[36:39]
	s_setprio 0
	s_setprio 1
	v_mfma_f32_16x16x32_bf16 v[32:35], v[150:153], v[180:183], v[32:35]
	v_mfma_f32_16x16x32_bf16 v[28:31], v[158:161], v[180:183], v[28:31]
	v_mfma_f32_16x16x32_bf16 v[24:27], v[150:153], v[194:197], v[24:27]
	v_mfma_f32_16x16x32_bf16 v[20:23], v[158:161], v[194:197], v[20:23]
	v_mfma_f32_16x16x32_bf16 v[16:19], v[150:153], v[202:205], v[16:19]
	v_mfma_f32_16x16x32_bf16 v[12:15], v[158:161], v[202:205], v[12:15]
	v_mfma_f32_16x16x32_bf16 v[8:11], v[150:153], v[216:219], v[8:11]
	v_mfma_f32_16x16x32_bf16 v[2:5], v[158:161], v[216:219], v[4:7]
	v_mfma_f32_16x16x32_bf16 v[32:35], v[154:157], v[190:193], v[32:35]
	v_mfma_f32_16x16x32_bf16 v[28:31], v[176:179], v[190:193], v[28:31]
	v_mfma_f32_16x16x32_bf16 v[24:27], v[154:157], v[198:201], v[24:27]
	v_mfma_f32_16x16x32_bf16 v[20:23], v[176:179], v[198:201], v[20:23]
	v_mfma_f32_16x16x32_bf16 v[16:19], v[154:157], v[206:209], v[16:19]
	v_mfma_f32_16x16x32_bf16 v[12:15], v[176:179], v[206:209], v[12:15]
	v_mfma_f32_16x16x32_bf16 v[8:11], v[154:157], v[220:223], v[8:11]
	v_mfma_f32_16x16x32_bf16 v[2:5], v[176:179], v[220:223], v[2:5]
	s_setprio 0
	s_barrier
	s_add_i32 s64, 0, 0x18000
	v_add_u32_e32 v0, s64, v185
	s_add_i32 s65, 0, 0x1c000
	ds_read_b128 v[134:137], v0
	ds_read_b128 v[138:141], v0 offset:1024
	ds_read_b128 v[142:145], v0 offset:2048
	ds_read_b128 v[146:149], v0 offset:3072
	v_add_u32_e32 v0, s65, v185
	ds_read_b128 v[150:153], v0
	ds_read_b128 v[154:157], v0 offset:1024
	ds_read_b128 v[158:161], v0 offset:2048
	ds_read_b128 v[176:179], v0 offset:3072
	s_add_u32 s40, s40, 0x80000
	s_addc_u32 s41, s41, 0
	s_mov_b32 m0, s50
	ds_read_b128 v[180:183], v187 offset:32768
	ds_read_b128 v[190:193], v187 offset:33792
	ds_read_b128 v[194:197], v187 offset:34816
	ds_read_b128 v[198:201], v187 offset:35840
	ds_read_b128 v[202:205], v187 offset:36864
	ds_read_b128 v[206:209], v187 offset:37888
	ds_read_b128 v[216:219], v187 offset:38912
	ds_read_b128 v[220:223], v187 offset:39936
	global_load_lds_dwordx4 v170, s[40:41]
	s_mov_b32 m0, s51
	s_nop 0
	global_load_lds_dwordx4 v166, s[40:41]
	s_waitcnt vmcnt(8)
	s_waitcnt lgkmcnt(0)
	s_barrier
	s_setprio 1
	s_waitcnt lgkmcnt(0)
	v_mfma_f32_16x16x32_bf16 v[128:131], v[134:137], v[180:183], v[128:131]
	v_mfma_f32_16x16x32_bf16 v[124:127], v[142:145], v[180:183], v[124:127]
	v_mfma_f32_16x16x32_bf16 v[120:123], v[134:137], v[194:197], v[120:123]
	v_mfma_f32_16x16x32_bf16 v[116:119], v[142:145], v[194:197], v[116:119]
	v_mfma_f32_16x16x32_bf16 v[112:115], v[134:137], v[202:205], v[112:115]
	v_mfma_f32_16x16x32_bf16 v[108:111], v[142:145], v[202:205], v[108:111]
	v_mfma_f32_16x16x32_bf16 v[104:107], v[134:137], v[216:219], v[104:107]
	v_mfma_f32_16x16x32_bf16 v[100:103], v[142:145], v[216:219], v[100:103]
	v_mfma_f32_16x16x32_bf16 v[128:131], v[138:141], v[190:193], v[128:131]
	v_mfma_f32_16x16x32_bf16 v[124:127], v[146:149], v[190:193], v[124:127]
	v_mfma_f32_16x16x32_bf16 v[120:123], v[138:141], v[198:201], v[120:123]
	v_mfma_f32_16x16x32_bf16 v[116:119], v[146:149], v[198:201], v[116:119]
	v_mfma_f32_16x16x32_bf16 v[112:115], v[138:141], v[206:209], v[112:115]
	v_mfma_f32_16x16x32_bf16 v[108:111], v[146:149], v[206:209], v[108:111]
	v_mfma_f32_16x16x32_bf16 v[104:107], v[138:141], v[220:223], v[104:107]
	v_mfma_f32_16x16x32_bf16 v[100:103], v[146:149], v[220:223], v[100:103]
	s_setprio 0
	s_setprio 1
	v_mfma_f32_16x16x32_bf16 v[96:99], v[150:153], v[180:183], v[96:99]
	v_mfma_f32_16x16x32_bf16 v[92:95], v[158:161], v[180:183], v[92:95]
	v_mfma_f32_16x16x32_bf16 v[88:91], v[150:153], v[194:197], v[88:91]
	v_mfma_f32_16x16x32_bf16 v[84:87], v[158:161], v[194:197], v[84:87]
	v_mfma_f32_16x16x32_bf16 v[80:83], v[150:153], v[202:205], v[80:83]
	v_mfma_f32_16x16x32_bf16 v[76:79], v[158:161], v[202:205], v[76:79]
	v_mfma_f32_16x16x32_bf16 v[72:75], v[150:153], v[216:219], v[72:75]
	v_mfma_f32_16x16x32_bf16 v[68:71], v[158:161], v[216:219], v[68:71]
	v_mfma_f32_16x16x32_bf16 v[96:99], v[154:157], v[190:193], v[96:99]
	v_mfma_f32_16x16x32_bf16 v[92:95], v[176:179], v[190:193], v[92:95]
	v_mfma_f32_16x16x32_bf16 v[88:91], v[154:157], v[198:201], v[88:91]
	v_mfma_f32_16x16x32_bf16 v[84:87], v[176:179], v[198:201], v[84:87]
	v_mfma_f32_16x16x32_bf16 v[80:83], v[154:157], v[206:209], v[80:83]
	v_mfma_f32_16x16x32_bf16 v[76:79], v[176:179], v[206:209], v[76:79]
	v_mfma_f32_16x16x32_bf16 v[72:75], v[154:157], v[220:223], v[72:75]
	v_mfma_f32_16x16x32_bf16 v[68:71], v[176:179], v[220:223], v[68:71]
	s_setprio 0
	s_barrier
	s_add_i32 s40, s64, s19
	v_lshl_add_u64 v[6:7], v[162:163], 0, s[22:23]
	s_mov_b32 m0, s40
	ds_read_b128 v[180:183], v187 offset:49152
	ds_read_b128 v[190:193], v187 offset:50176
	ds_read_b128 v[194:197], v187 offset:51200
	ds_read_b128 v[198:201], v187 offset:52224
	ds_read_b128 v[202:205], v187 offset:53248
	ds_read_b128 v[206:209], v187 offset:54272
	ds_read_b128 v[216:219], v187 offset:55296
	ds_read_b128 v[220:223], v187 offset:56320
	global_load_lds_dwordx4 v[6:7], off
	s_add_i32 m0, s40, 0x2000
	s_add_u32 s30, s30, 0x80080
	v_lshl_add_u64 v[6:7], v[240:241], 0, s[22:23]
	s_addc_u32 s31, s31, 0
	s_add_i32 s40, s65, s19
	global_load_lds_dwordx4 v[6:7], off
	s_mov_b32 m0, s40
	s_nop 0
	global_load_lds_dwordx4 v168, s[30:31]
	s_add_i32 m0, s40, 0x2000
	s_nop 0
	global_load_lds_dwordx4 v164, s[30:31]
	v_lshl_add_u64 v[6:7], v[242:243], 0, s[22:23]
	s_mov_b32 m0, s52
	s_nop 0
	global_load_lds_dwordx4 v[6:7], off
	v_lshl_add_u64 v[6:7], v[244:245], 0, s[22:23]
	s_mov_b32 m0, s53
	s_nop 0
	global_load_lds_dwordx4 v[6:7], off
	s_waitcnt vmcnt(8)
	s_waitcnt lgkmcnt(0)
	s_barrier
	s_setprio 1
	s_waitcnt lgkmcnt(0)
	v_mfma_f32_16x16x32_bf16 v[64:67], v[134:137], v[180:183], v[64:67]
	v_mfma_f32_16x16x32_bf16 v[60:63], v[142:145], v[180:183], v[60:63]
	v_mfma_f32_16x16x32_bf16 v[56:59], v[134:137], v[194:197], v[56:59]
	v_mfma_f32_16x16x32_bf16 v[52:55], v[142:145], v[194:197], v[52:55]
	v_mfma_f32_16x16x32_bf16 v[48:51], v[134:137], v[202:205], v[48:51]
	v_mfma_f32_16x16x32_bf16 v[44:47], v[142:145], v[202:205], v[44:47]
	v_mfma_f32_16x16x32_bf16 v[40:43], v[134:137], v[216:219], v[40:43]
	v_mfma_f32_16x16x32_bf16 v[36:39], v[142:145], v[216:219], v[36:39]
	v_mfma_f32_16x16x32_bf16 v[64:67], v[138:141], v[190:193], v[64:67]
	v_mfma_f32_16x16x32_bf16 v[60:63], v[146:149], v[190:193], v[60:63]
	v_mfma_f32_16x16x32_bf16 v[56:59], v[138:141], v[198:201], v[56:59]
	v_mfma_f32_16x16x32_bf16 v[52:55], v[146:149], v[198:201], v[52:55]
	v_mfma_f32_16x16x32_bf16 v[48:51], v[138:141], v[206:209], v[48:51]
	v_mfma_f32_16x16x32_bf16 v[44:47], v[146:149], v[206:209], v[44:47]
	v_mfma_f32_16x16x32_bf16 v[40:43], v[138:141], v[220:223], v[40:43]
	v_mfma_f32_16x16x32_bf16 v[36:39], v[146:149], v[220:223], v[36:39]
	s_setprio 0
	s_setprio 1
	v_mfma_f32_16x16x32_bf16 v[32:35], v[150:153], v[180:183], v[32:35]
	v_mfma_f32_16x16x32_bf16 v[28:31], v[158:161], v[180:183], v[28:31]
	v_mfma_f32_16x16x32_bf16 v[24:27], v[150:153], v[194:197], v[24:27]
	v_mfma_f32_16x16x32_bf16 v[20:23], v[158:161], v[194:197], v[20:23]
	v_mfma_f32_16x16x32_bf16 v[16:19], v[150:153], v[202:205], v[16:19]
	v_mfma_f32_16x16x32_bf16 v[12:15], v[158:161], v[202:205], v[12:15]
	v_mfma_f32_16x16x32_bf16 v[6:9], v[150:153], v[216:219], v[8:11]
	v_mfma_f32_16x16x32_bf16 v[2:5], v[158:161], v[216:219], v[2:5]
	v_mfma_f32_16x16x32_bf16 v[32:35], v[154:157], v[190:193], v[32:35]
	v_mfma_f32_16x16x32_bf16 v[28:31], v[176:179], v[190:193], v[28:31]
	v_mfma_f32_16x16x32_bf16 v[24:27], v[154:157], v[198:201], v[24:27]
	v_mfma_f32_16x16x32_bf16 v[20:23], v[176:179], v[198:201], v[20:23]
	v_mfma_f32_16x16x32_bf16 v[16:19], v[154:157], v[206:209], v[16:19]
	v_mfma_f32_16x16x32_bf16 v[12:15], v[176:179], v[206:209], v[12:15]
	v_mfma_f32_16x16x32_bf16 v[8:11], v[154:157], v[220:223], v[6:9]
	v_mfma_f32_16x16x32_bf16 v[4:7], v[176:179], v[220:223], v[2:5]
	s_setprio 0
	s_barrier
	s_add_u32 s2, s2, 0x100
	s_addc_u32 s3, s3, 0
	s_add_u32 s61, s61, 0x100
	s_addc_u32 s62, s62, 0
	s_cmp_ge_i32 s63, s56
	s_mov_b32 s30, s63
	s_cbranch_scc0 .LBB0_1493
	s_and_b64 vcc, exec, s[6:7]
	s_cbranch_vccz .LBB0_1496
	s_barrier

.LBB0_1575:
	s_add_u32 s50, s48, 0xfff80080
	s_addc_u32 s51, s49, -1
	s_add_i32 s68, 0, 0x10000
	s_cmp_eq_u32 s67, 28
	s_cselect_b32 s53, s43, s51
	s_cselect_b32 s52, s63, s50
	s_cselect_b32 s51, s37, s66
	s_cselect_b32 s50, s64, s65
	s_add_i32 s70, 0, 0x14000
	v_add_u32_e32 v142, s68, v165
	v_add_u32_e32 v172, s70, v165
	ds_read_b128 v[130:133], v142
	ds_read_b128 v[134:137], v142 offset:1024
	ds_read_b128 v[138:141], v142 offset:2048
	ds_read_b128 v[142:145], v142 offset:3072
	ds_read_b128 v[156:159], v172
	ds_read_b128 v[160:163], v172 offset:1024
	ds_read_b128 v[168:171], v172 offset:2048
	ds_read_b128 v[172:175], v172 offset:3072
	s_add_i32 m0, s54, 0xc000
	ds_read_b128 v[176:179], v167
	ds_read_b128 v[180:183], v167 offset:1024
	ds_read_b128 v[184:187], v167 offset:2048
	ds_read_b128 v[188:191], v167 offset:3072
	ds_read_b128 v[192:195], v167 offset:4096
	ds_read_b128 v[196:199], v167 offset:5120
	ds_read_b128 v[200:203], v167 offset:6144
	ds_read_b128 v[204:207], v167 offset:7168
	global_load_lds_dwordx4 v152, s[48:49]
	s_add_i32 m0, s54, 0xe000
	s_nop 0
	global_load_lds_dwordx4 v154, s[48:49]
	s_waitcnt vmcnt(8)
	s_waitcnt lgkmcnt(0)
	s_barrier
	s_setprio 1
	s_waitcnt lgkmcnt(0)
	v_mfma_f32_16x16x32_bf16 v[126:129], v[130:133], v[176:179], v[126:129]
	v_mfma_f32_16x16x32_bf16 v[122:125], v[138:141], v[176:179], v[122:125]
	v_mfma_f32_16x16x32_bf16 v[110:113], v[130:133], v[184:187], v[110:113]
	v_mfma_f32_16x16x32_bf16 v[106:109], v[138:141], v[184:187], v[106:109]
	v_mfma_f32_16x16x32_bf16 v[94:97], v[130:133], v[192:195], v[94:97]
	v_mfma_f32_16x16x32_bf16 v[90:93], v[138:141], v[192:195], v[90:93]
	v_mfma_f32_16x16x32_bf16 v[78:81], v[130:133], v[200:203], v[78:81]
	v_mfma_f32_16x16x32_bf16 v[74:77], v[138:141], v[200:203], v[74:77]
	v_mfma_f32_16x16x32_bf16 v[126:129], v[134:137], v[180:183], v[126:129]
	v_mfma_f32_16x16x32_bf16 v[122:125], v[142:145], v[180:183], v[122:125]
	v_mfma_f32_16x16x32_bf16 v[110:113], v[134:137], v[188:191], v[110:113]
	v_mfma_f32_16x16x32_bf16 v[106:109], v[142:145], v[188:191], v[106:109]
	v_mfma_f32_16x16x32_bf16 v[94:97], v[134:137], v[196:199], v[94:97]
	v_mfma_f32_16x16x32_bf16 v[90:93], v[142:145], v[196:199], v[90:93]
	v_mfma_f32_16x16x32_bf16 v[78:81], v[134:137], v[204:207], v[78:81]
	v_mfma_f32_16x16x32_bf16 v[74:77], v[142:145], v[204:207], v[74:77]
	s_setprio 0
	s_setprio 1
	v_mfma_f32_16x16x32_bf16 v[118:121], v[156:159], v[176:179], v[118:121]
	v_mfma_f32_16x16x32_bf16 v[114:117], v[168:171], v[176:179], v[114:117]
	v_mfma_f32_16x16x32_bf16 v[102:105], v[156:159], v[184:187], v[102:105]
	v_mfma_f32_16x16x32_bf16 v[98:101], v[168:171], v[184:187], v[98:101]
	v_mfma_f32_16x16x32_bf16 v[86:89], v[156:159], v[192:195], v[86:89]
	v_mfma_f32_16x16x32_bf16 v[82:85], v[168:171], v[192:195], v[82:85]
	v_mfma_f32_16x16x32_bf16 v[70:73], v[156:159], v[200:203], v[70:73]
	v_mfma_f32_16x16x32_bf16 v[66:69], v[168:171], v[200:203], v[66:69]
	v_mfma_f32_16x16x32_bf16 v[118:121], v[160:163], v[180:183], v[118:121]
	v_mfma_f32_16x16x32_bf16 v[114:117], v[172:175], v[180:183], v[114:117]
	v_mfma_f32_16x16x32_bf16 v[102:105], v[160:163], v[188:191], v[102:105]
	v_mfma_f32_16x16x32_bf16 v[98:101], v[172:175], v[188:191], v[98:101]
	v_mfma_f32_16x16x32_bf16 v[86:89], v[160:163], v[196:199], v[86:89]
	v_mfma_f32_16x16x32_bf16 v[82:85], v[172:175], v[196:199], v[82:85]
	v_mfma_f32_16x16x32_bf16 v[70:73], v[160:163], v[204:207], v[70:73]
	v_mfma_f32_16x16x32_bf16 v[66:69], v[172:175], v[204:207], v[66:69]
	s_setprio 0
	s_barrier
	s_add_i32 s68, s68, s19
	v_lshl_add_u64 v[208:209], s[50:51], 0, v[0:1]
	s_mov_b32 m0, s68
	ds_read_b128 v[176:179], v167 offset:16384
	ds_read_b128 v[180:183], v167 offset:17408
	ds_read_b128 v[184:187], v167 offset:18432
	ds_read_b128 v[188:191], v167 offset:19456
	ds_read_b128 v[192:195], v167 offset:20480
	ds_read_b128 v[196:199], v167 offset:21504
	ds_read_b128 v[200:203], v167 offset:22528
	ds_read_b128 v[204:207], v167 offset:23552
	global_load_lds_dwordx4 v0, s[50:51]
	s_add_i32 m0, s68, 0x2000
	s_add_u32 s68, s50, 0x80000
	v_lshl_add_u64 v[216:217], s[50:51], 0, v[146:147]
	s_addc_u32 s69, s51, 0
	s_add_i32 s70, s70, s19
	global_load_lds_dwordx4 v146, s[50:51]
	s_mov_b32 m0, s70
	v_lshl_add_u64 v[220:221], s[52:53], 0, v[148:149]
	global_load_lds_dwordx4 v0, s[68:69]
	s_add_i32 m0, s70, 0x2000
	s_nop 0
	global_load_lds_dwordx4 v146, s[68:69]
	v_lshl_add_u64 v[218:219], s[52:53], 0, v[150:151]
	s_mov_b32 m0, s54
	s_nop 0
	global_load_lds_dwordx4 v150, s[52:53]
	s_mov_b32 m0, s55
	s_nop 0
	global_load_lds_dwordx4 v148, s[52:53]
	s_waitcnt vmcnt(8)
	s_waitcnt lgkmcnt(0)
	s_barrier
	s_setprio 1
	s_waitcnt lgkmcnt(0)
	v_mfma_f32_16x16x32_bf16 v[62:65], v[130:133], v[176:179], v[62:65]
	v_mfma_f32_16x16x32_bf16 v[58:61], v[138:141], v[176:179], v[58:61]
	v_mfma_f32_16x16x32_bf16 v[46:49], v[130:133], v[184:187], v[46:49]
	v_mfma_f32_16x16x32_bf16 v[42:45], v[138:141], v[184:187], v[42:45]
	v_mfma_f32_16x16x32_bf16 v[30:33], v[130:133], v[192:195], v[30:33]
	v_mfma_f32_16x16x32_bf16 v[26:29], v[138:141], v[192:195], v[26:29]
	v_mfma_f32_16x16x32_bf16 v[14:17], v[130:133], v[200:203], v[14:17]
	v_mfma_f32_16x16x32_bf16 v[10:13], v[138:141], v[200:203], v[10:13]
	v_mfma_f32_16x16x32_bf16 v[62:65], v[134:137], v[180:183], v[62:65]
	v_mfma_f32_16x16x32_bf16 v[58:61], v[142:145], v[180:183], v[58:61]
	v_mfma_f32_16x16x32_bf16 v[46:49], v[134:137], v[188:191], v[46:49]
	v_mfma_f32_16x16x32_bf16 v[42:45], v[142:145], v[188:191], v[42:45]
	v_mfma_f32_16x16x32_bf16 v[30:33], v[134:137], v[196:199], v[30:33]
	v_mfma_f32_16x16x32_bf16 v[26:29], v[142:145], v[196:199], v[26:29]
	v_mfma_f32_16x16x32_bf16 v[14:17], v[134:137], v[204:207], v[14:17]
	v_mfma_f32_16x16x32_bf16 v[10:13], v[142:145], v[204:207], v[10:13]
	s_setprio 0
	s_setprio 1
	v_mfma_f32_16x16x32_bf16 v[54:57], v[156:159], v[176:179], v[54:57]
	v_mfma_f32_16x16x32_bf16 v[50:53], v[168:171], v[176:179], v[50:53]
	v_mfma_f32_16x16x32_bf16 v[38:41], v[156:159], v[184:187], v[38:41]
	v_mfma_f32_16x16x32_bf16 v[34:37], v[168:171], v[184:187], v[34:37]
	v_mfma_f32_16x16x32_bf16 v[22:25], v[156:159], v[192:195], v[22:25]
	v_mfma_f32_16x16x32_bf16 v[18:21], v[168:171], v[192:195], v[18:21]
	v_mfma_f32_16x16x32_bf16 v[6:9], v[156:159], v[200:203], v[6:9]
	v_mfma_f32_16x16x32_bf16 v[2:5], v[168:171], v[200:203], v[2:5]
	v_mfma_f32_16x16x32_bf16 v[54:57], v[160:163], v[180:183], v[54:57]
	v_mfma_f32_16x16x32_bf16 v[50:53], v[172:175], v[180:183], v[50:53]
	v_mfma_f32_16x16x32_bf16 v[38:41], v[160:163], v[188:191], v[38:41]
	v_mfma_f32_16x16x32_bf16 v[34:37], v[172:175], v[188:191], v[34:37]
	v_mfma_f32_16x16x32_bf16 v[22:25], v[160:163], v[196:199], v[22:25]
	v_mfma_f32_16x16x32_bf16 v[18:21], v[172:175], v[196:199], v[18:21]
	v_mfma_f32_16x16x32_bf16 v[6:9], v[160:163], v[204:207], v[6:9]
	v_mfma_f32_16x16x32_bf16 v[2:5], v[172:175], v[204:207], v[2:5]
	s_setprio 0
	s_barrier
	s_add_i32 s68, 0, 0x18000
	s_add_i32 s69, 0, 0x1c000
	v_add_u32_e32 v142, s68, v165
	v_add_u32_e32 v172, s69, v165
	ds_read_b128 v[130:133], v142
	ds_read_b128 v[134:137], v142 offset:1024
	ds_read_b128 v[138:141], v142 offset:2048
	ds_read_b128 v[142:145], v142 offset:3072
	ds_read_b128 v[156:159], v172
	ds_read_b128 v[160:163], v172 offset:1024
	ds_read_b128 v[168:171], v172 offset:2048
	ds_read_b128 v[172:175], v172 offset:3072
	s_add_u32 s52, s52, 0x80000
	s_addc_u32 s53, s53, 0
	s_mov_b32 m0, s56
	ds_read_b128 v[176:179], v167 offset:32768
	ds_read_b128 v[180:183], v167 offset:33792
	ds_read_b128 v[184:187], v167 offset:34816
	ds_read_b128 v[188:191], v167 offset:35840
	ds_read_b128 v[192:195], v167 offset:36864
	ds_read_b128 v[196:199], v167 offset:37888
	ds_read_b128 v[200:203], v167 offset:38912
	ds_read_b128 v[204:207], v167 offset:39936
	global_load_lds_dwordx4 v150, s[52:53]
	s_mov_b32 m0, s57
	s_nop 0
	global_load_lds_dwordx4 v148, s[52:53]
	s_waitcnt vmcnt(8)
	s_waitcnt lgkmcnt(0)
	s_barrier
	s_setprio 1
	s_waitcnt lgkmcnt(0)
	v_mfma_f32_16x16x32_bf16 v[126:129], v[130:133], v[176:179], v[126:129]
	v_mfma_f32_16x16x32_bf16 v[122:125], v[138:141], v[176:179], v[122:125]
	v_mfma_f32_16x16x32_bf16 v[110:113], v[130:133], v[184:187], v[110:113]
	v_mfma_f32_16x16x32_bf16 v[106:109], v[138:141], v[184:187], v[106:109]
	v_mfma_f32_16x16x32_bf16 v[94:97], v[130:133], v[192:195], v[94:97]
	v_mfma_f32_16x16x32_bf16 v[90:93], v[138:141], v[192:195], v[90:93]
	v_mfma_f32_16x16x32_bf16 v[78:81], v[130:133], v[200:203], v[78:81]
	v_mfma_f32_16x16x32_bf16 v[74:77], v[138:141], v[200:203], v[74:77]
	v_mfma_f32_16x16x32_bf16 v[126:129], v[134:137], v[180:183], v[126:129]
	v_mfma_f32_16x16x32_bf16 v[122:125], v[142:145], v[180:183], v[122:125]
	v_mfma_f32_16x16x32_bf16 v[110:113], v[134:137], v[188:191], v[110:113]
	v_mfma_f32_16x16x32_bf16 v[106:109], v[142:145], v[188:191], v[106:109]
	v_mfma_f32_16x16x32_bf16 v[94:97], v[134:137], v[196:199], v[94:97]
	v_mfma_f32_16x16x32_bf16 v[90:93], v[142:145], v[196:199], v[90:93]
	v_mfma_f32_16x16x32_bf16 v[78:81], v[134:137], v[204:207], v[78:81]
	v_mfma_f32_16x16x32_bf16 v[74:77], v[142:145], v[204:207], v[74:77]
	s_setprio 0
	s_setprio 1
	v_mfma_f32_16x16x32_bf16 v[118:121], v[156:159], v[176:179], v[118:121]
	v_mfma_f32_16x16x32_bf16 v[114:117], v[168:171], v[176:179], v[114:117]
	v_mfma_f32_16x16x32_bf16 v[102:105], v[156:159], v[184:187], v[102:105]
	v_mfma_f32_16x16x32_bf16 v[98:101], v[168:171], v[184:187], v[98:101]
	v_mfma_f32_16x16x32_bf16 v[86:89], v[156:159], v[192:195], v[86:89]
	v_mfma_f32_16x16x32_bf16 v[82:85], v[168:171], v[192:195], v[82:85]
	v_mfma_f32_16x16x32_bf16 v[70:73], v[156:159], v[200:203], v[70:73]
	v_mfma_f32_16x16x32_bf16 v[66:69], v[168:171], v[200:203], v[66:69]
	v_mfma_f32_16x16x32_bf16 v[118:121], v[160:163], v[180:183], v[118:121]
	v_mfma_f32_16x16x32_bf16 v[114:117], v[172:175], v[180:183], v[114:117]
	v_mfma_f32_16x16x32_bf16 v[102:105], v[160:163], v[188:191], v[102:105]
	v_mfma_f32_16x16x32_bf16 v[98:101], v[172:175], v[188:191], v[98:101]
	v_mfma_f32_16x16x32_bf16 v[86:89], v[160:163], v[196:199], v[86:89]
	v_mfma_f32_16x16x32_bf16 v[82:85], v[172:175], v[196:199], v[82:85]
	v_mfma_f32_16x16x32_bf16 v[70:73], v[160:163], v[204:207], v[70:73]
	v_mfma_f32_16x16x32_bf16 v[66:69], v[172:175], v[204:207], v[66:69]
	s_setprio 0
	s_barrier
	s_add_i32 s52, s68, s19
	v_lshl_add_u64 v[208:209], v[208:209], 0, s[22:23]
	s_mov_b32 m0, s52
	ds_read_b128 v[176:179], v167 offset:49152
	ds_read_b128 v[180:183], v167 offset:50176
	ds_read_b128 v[184:187], v167 offset:51200
	ds_read_b128 v[188:191], v167 offset:52224
	ds_read_b128 v[192:195], v167 offset:53248
	ds_read_b128 v[196:199], v167 offset:54272
	ds_read_b128 v[200:203], v167 offset:55296
	ds_read_b128 v[204:207], v167 offset:56320
	global_load_lds_dwordx4 v[208:209], off
	s_add_i32 m0, s52, 0x2000
	s_add_u32 s50, s50, 0x80080
	v_lshl_add_u64 v[208:209], v[216:217], 0, s[22:23]
	s_addc_u32 s51, s51, 0
	s_add_i32 s52, s69, s19
	global_load_lds_dwordx4 v[208:209], off
	s_mov_b32 m0, s52
	s_nop 0
	global_load_lds_dwordx4 v0, s[50:51]
	s_add_i32 m0, s52, 0x2000
	s_nop 0
	global_load_lds_dwordx4 v146, s[50:51]
	v_lshl_add_u64 v[208:209], v[218:219], 0, s[22:23]
	s_mov_b32 m0, s59
	s_nop 0
	global_load_lds_dwordx4 v[208:209], off
	v_lshl_add_u64 v[208:209], v[220:221], 0, s[22:23]
	s_mov_b32 m0, s60
	s_nop 0
	global_load_lds_dwordx4 v[208:209], off
	s_waitcnt vmcnt(8)
	s_waitcnt lgkmcnt(0)
	s_barrier
	s_setprio 1
	s_waitcnt lgkmcnt(0)
	v_mfma_f32_16x16x32_bf16 v[62:65], v[130:133], v[176:179], v[62:65]
	v_mfma_f32_16x16x32_bf16 v[58:61], v[138:141], v[176:179], v[58:61]
	v_mfma_f32_16x16x32_bf16 v[46:49], v[130:133], v[184:187], v[46:49]
	v_mfma_f32_16x16x32_bf16 v[42:45], v[138:141], v[184:187], v[42:45]
	v_mfma_f32_16x16x32_bf16 v[30:33], v[130:133], v[192:195], v[30:33]
	v_mfma_f32_16x16x32_bf16 v[26:29], v[138:141], v[192:195], v[26:29]
	v_mfma_f32_16x16x32_bf16 v[14:17], v[130:133], v[200:203], v[14:17]
	v_mfma_f32_16x16x32_bf16 v[10:13], v[138:141], v[200:203], v[10:13]
	v_mfma_f32_16x16x32_bf16 v[62:65], v[134:137], v[180:183], v[62:65]
	v_mfma_f32_16x16x32_bf16 v[58:61], v[142:145], v[180:183], v[58:61]
	v_mfma_f32_16x16x32_bf16 v[46:49], v[134:137], v[188:191], v[46:49]
	v_mfma_f32_16x16x32_bf16 v[42:45], v[142:145], v[188:191], v[42:45]
	v_mfma_f32_16x16x32_bf16 v[30:33], v[134:137], v[196:199], v[30:33]
	v_mfma_f32_16x16x32_bf16 v[26:29], v[142:145], v[196:199], v[26:29]
	v_mfma_f32_16x16x32_bf16 v[14:17], v[134:137], v[204:207], v[14:17]
	v_mfma_f32_16x16x32_bf16 v[10:13], v[142:145], v[204:207], v[10:13]
	s_setprio 0
	s_setprio 1
	v_mfma_f32_16x16x32_bf16 v[54:57], v[156:159], v[176:179], v[54:57]
	v_mfma_f32_16x16x32_bf16 v[50:53], v[168:171], v[176:179], v[50:53]
	v_mfma_f32_16x16x32_bf16 v[38:41], v[156:159], v[184:187], v[38:41]
	v_mfma_f32_16x16x32_bf16 v[34:37], v[168:171], v[184:187], v[34:37]
	v_mfma_f32_16x16x32_bf16 v[22:25], v[156:159], v[192:195], v[22:25]
	v_mfma_f32_16x16x32_bf16 v[18:21], v[168:171], v[192:195], v[18:21]
	v_mfma_f32_16x16x32_bf16 v[6:9], v[156:159], v[200:203], v[6:9]
	v_mfma_f32_16x16x32_bf16 v[2:5], v[168:171], v[200:203], v[2:5]
	v_mfma_f32_16x16x32_bf16 v[54:57], v[160:163], v[180:183], v[54:57]
	v_mfma_f32_16x16x32_bf16 v[50:53], v[172:175], v[180:183], v[50:53]
	v_mfma_f32_16x16x32_bf16 v[38:41], v[160:163], v[188:191], v[38:41]
	v_mfma_f32_16x16x32_bf16 v[34:37], v[172:175], v[188:191], v[34:37]
	v_mfma_f32_16x16x32_bf16 v[22:25], v[160:163], v[196:199], v[22:25]
	v_mfma_f32_16x16x32_bf16 v[18:21], v[172:175], v[196:199], v[18:21]
	v_mfma_f32_16x16x32_bf16 v[6:9], v[160:163], v[204:207], v[6:9]
	v_mfma_f32_16x16x32_bf16 v[2:5], v[172:175], v[204:207], v[2:5]
	s_setprio 0
	s_barrier
	s_add_i32 s67, s67, 2
	s_add_u32 s48, s48, 0x100
	s_addc_u32 s49, s49, 0
	s_add_u32 s65, s65, 0x100
	s_addc_u32 s66, s66, 0
	s_cmp_gt_u32 s67, 29
	s_cbranch_scc0 .LBB0_1575
	s_and_b64 vcc, exec, s[30:31]
	s_cbranch_vccz .LBB0_1578
	s_barrier

.LBB0_1667:
	s_add_u32 s46, s0, 0xfff80080
	s_addc_u32 s47, s1, -1
	s_add_i32 s63, 0, 0x10000
	s_cmp_eq_u32 s62, 28
	s_cselect_b32 s49, s41, s47
	s_cselect_b32 s48, s58, s46
	v_add_u32_e32 v150, s63, v157
	s_cselect_b32 s47, s37, s61
	s_cselect_b32 s46, s59, s60
	s_add_i32 s66, 0, 0x14000
	ds_read_b128 v[130:133], v150
	ds_read_b128 v[134:137], v150 offset:1024
	ds_read_b128 v[160:163], v150 offset:2048
	ds_read_b128 v[168:171], v150 offset:3072
	v_add_u32_e32 v150, s66, v157
	ds_read_b128 v[172:175], v150
	ds_read_b128 v[176:179], v150 offset:1024
	ds_read_b128 v[180:183], v150 offset:2048
	ds_read_b128 v[184:187], v150 offset:3072
	s_add_i32 m0, s24, 0xc000
	ds_read_b128 v[188:191], v167
	ds_read_b128 v[192:195], v167 offset:1024
	ds_read_b128 v[196:199], v167 offset:2048
	ds_read_b128 v[200:203], v167 offset:3072
	ds_read_b128 v[204:207], v167 offset:4096
	ds_read_b128 v[216:219], v167 offset:5120
	ds_read_b128 v[220:223], v167 offset:6144
	ds_read_b128 v[240:243], v167 offset:7168
	global_load_lds_dwordx4 v146, s[0:1]
	s_add_i32 m0, s24, 0xe000
	s_nop 0
	global_load_lds_dwordx4 v148, s[0:1]
	s_waitcnt vmcnt(8)
	s_waitcnt lgkmcnt(0)
	s_barrier
	s_setprio 1
	s_waitcnt lgkmcnt(0)
	v_mfma_f32_16x16x32_bf16 v[126:129], v[130:133], v[188:191], v[126:129]
	v_mfma_f32_16x16x32_bf16 v[122:125], v[160:163], v[188:191], v[122:125]
	v_mfma_f32_16x16x32_bf16 v[110:113], v[130:133], v[196:199], v[110:113]
	v_mfma_f32_16x16x32_bf16 v[106:109], v[160:163], v[196:199], v[106:109]
	v_mfma_f32_16x16x32_bf16 v[94:97], v[130:133], v[204:207], v[94:97]
	v_mfma_f32_16x16x32_bf16 v[90:93], v[160:163], v[204:207], v[90:93]
	v_mfma_f32_16x16x32_bf16 v[78:81], v[130:133], v[220:223], v[78:81]
	v_mfma_f32_16x16x32_bf16 v[74:77], v[160:163], v[220:223], v[74:77]
	v_mfma_f32_16x16x32_bf16 v[126:129], v[134:137], v[192:195], v[126:129]
	v_mfma_f32_16x16x32_bf16 v[122:125], v[168:171], v[192:195], v[122:125]
	v_mfma_f32_16x16x32_bf16 v[110:113], v[134:137], v[200:203], v[110:113]
	v_mfma_f32_16x16x32_bf16 v[106:109], v[168:171], v[200:203], v[106:109]
	v_mfma_f32_16x16x32_bf16 v[94:97], v[134:137], v[216:219], v[94:97]
	v_mfma_f32_16x16x32_bf16 v[90:93], v[168:171], v[216:219], v[90:93]
	v_mfma_f32_16x16x32_bf16 v[78:81], v[134:137], v[240:243], v[78:81]
	v_mfma_f32_16x16x32_bf16 v[74:77], v[168:171], v[240:243], v[74:77]
	s_setprio 0
	s_setprio 1
	v_mfma_f32_16x16x32_bf16 v[118:121], v[172:175], v[188:191], v[118:121]
	v_mfma_f32_16x16x32_bf16 v[114:117], v[180:183], v[188:191], v[114:117]
	v_mfma_f32_16x16x32_bf16 v[102:105], v[172:175], v[196:199], v[102:105]
	v_mfma_f32_16x16x32_bf16 v[98:101], v[180:183], v[196:199], v[98:101]
	v_mfma_f32_16x16x32_bf16 v[86:89], v[172:175], v[204:207], v[86:89]
	v_mfma_f32_16x16x32_bf16 v[82:85], v[180:183], v[204:207], v[82:85]
	v_mfma_f32_16x16x32_bf16 v[70:73], v[172:175], v[220:223], v[70:73]
	v_mfma_f32_16x16x32_bf16 v[66:69], v[180:183], v[220:223], v[66:69]
	v_mfma_f32_16x16x32_bf16 v[118:121], v[176:179], v[192:195], v[118:121]
	v_mfma_f32_16x16x32_bf16 v[114:117], v[184:187], v[192:195], v[114:117]
	v_mfma_f32_16x16x32_bf16 v[102:105], v[176:179], v[200:203], v[102:105]
	v_mfma_f32_16x16x32_bf16 v[98:101], v[184:187], v[200:203], v[98:101]
	v_mfma_f32_16x16x32_bf16 v[86:89], v[176:179], v[216:219], v[86:89]
	v_mfma_f32_16x16x32_bf16 v[82:85], v[184:187], v[216:219], v[82:85]
	v_mfma_f32_16x16x32_bf16 v[70:73], v[176:179], v[240:243], v[70:73]
	v_mfma_f32_16x16x32_bf16 v[66:69], v[184:187], v[240:243], v[66:69]
	s_setprio 0
	s_barrier
	s_add_i32 s63, s63, s19
	v_lshl_add_u64 v[150:151], s[46:47], 0, v[0:1]
	s_mov_b32 m0, s63
	ds_read_b128 v[188:191], v167 offset:16384
	ds_read_b128 v[192:195], v167 offset:17408
	ds_read_b128 v[196:199], v167 offset:18432
	ds_read_b128 v[200:203], v167 offset:19456
	ds_read_b128 v[204:207], v167 offset:20480
	ds_read_b128 v[216:219], v167 offset:21504
	ds_read_b128 v[220:223], v167 offset:22528
	ds_read_b128 v[240:243], v167 offset:23552
	global_load_lds_dwordx4 v0, s[46:47]
	s_add_i32 m0, s63, 0x2000
	s_add_u32 s64, s46, 0x80000
	v_lshl_add_u64 v[154:155], s[46:47], 0, v[138:139]
	s_addc_u32 s65, s47, 0
	s_add_i32 s63, s66, s19
	global_load_lds_dwordx4 v138, s[46:47]
	s_mov_b32 m0, s63
	v_lshl_add_u64 v[208:209], s[48:49], 0, v[140:141]
	global_load_lds_dwordx4 v0, s[64:65]
	s_add_i32 m0, s63, 0x2000
	s_nop 0
	global_load_lds_dwordx4 v138, s[64:65]
	v_lshl_add_u64 v[164:165], s[48:49], 0, v[142:143]
	s_mov_b32 m0, s24
	s_nop 0
	global_load_lds_dwordx4 v142, s[48:49]
	s_mov_b32 m0, s50
	s_nop 0
	global_load_lds_dwordx4 v140, s[48:49]
	s_waitcnt vmcnt(8)
	s_waitcnt lgkmcnt(0)
	s_barrier
	s_setprio 1
	s_waitcnt lgkmcnt(0)
	v_mfma_f32_16x16x32_bf16 v[62:65], v[130:133], v[188:191], v[62:65]
	v_mfma_f32_16x16x32_bf16 v[58:61], v[160:163], v[188:191], v[58:61]
	v_mfma_f32_16x16x32_bf16 v[46:49], v[130:133], v[196:199], v[46:49]
	v_mfma_f32_16x16x32_bf16 v[42:45], v[160:163], v[196:199], v[42:45]
	v_mfma_f32_16x16x32_bf16 v[30:33], v[130:133], v[204:207], v[30:33]
	v_mfma_f32_16x16x32_bf16 v[26:29], v[160:163], v[204:207], v[26:29]
	v_mfma_f32_16x16x32_bf16 v[14:17], v[130:133], v[220:223], v[14:17]
	v_mfma_f32_16x16x32_bf16 v[10:13], v[160:163], v[220:223], v[10:13]
	v_mfma_f32_16x16x32_bf16 v[62:65], v[134:137], v[192:195], v[62:65]
	v_mfma_f32_16x16x32_bf16 v[58:61], v[168:171], v[192:195], v[58:61]
	v_mfma_f32_16x16x32_bf16 v[46:49], v[134:137], v[200:203], v[46:49]
	v_mfma_f32_16x16x32_bf16 v[42:45], v[168:171], v[200:203], v[42:45]
	v_mfma_f32_16x16x32_bf16 v[30:33], v[134:137], v[216:219], v[30:33]
	v_mfma_f32_16x16x32_bf16 v[26:29], v[168:171], v[216:219], v[26:29]
	v_mfma_f32_16x16x32_bf16 v[14:17], v[134:137], v[240:243], v[14:17]
	v_mfma_f32_16x16x32_bf16 v[10:13], v[168:171], v[240:243], v[10:13]
	s_setprio 0
	s_setprio 1
	v_mfma_f32_16x16x32_bf16 v[54:57], v[172:175], v[188:191], v[54:57]
	v_mfma_f32_16x16x32_bf16 v[50:53], v[180:183], v[188:191], v[50:53]
	v_mfma_f32_16x16x32_bf16 v[38:41], v[172:175], v[196:199], v[38:41]
	v_mfma_f32_16x16x32_bf16 v[34:37], v[180:183], v[196:199], v[34:37]
	v_mfma_f32_16x16x32_bf16 v[22:25], v[172:175], v[204:207], v[22:25]
	v_mfma_f32_16x16x32_bf16 v[18:21], v[180:183], v[204:207], v[18:21]
	v_mfma_f32_16x16x32_bf16 v[6:9], v[172:175], v[220:223], v[6:9]
	v_mfma_f32_16x16x32_bf16 v[2:5], v[180:183], v[220:223], v[2:5]
	v_mfma_f32_16x16x32_bf16 v[54:57], v[176:179], v[192:195], v[54:57]
	v_mfma_f32_16x16x32_bf16 v[50:53], v[184:187], v[192:195], v[50:53]
	v_mfma_f32_16x16x32_bf16 v[38:41], v[176:179], v[200:203], v[38:41]
	v_mfma_f32_16x16x32_bf16 v[34:37], v[184:187], v[200:203], v[34:37]
	v_mfma_f32_16x16x32_bf16 v[22:25], v[176:179], v[216:219], v[22:25]
	v_mfma_f32_16x16x32_bf16 v[18:21], v[184:187], v[216:219], v[18:21]
	v_mfma_f32_16x16x32_bf16 v[6:9], v[176:179], v[240:243], v[6:9]
	v_mfma_f32_16x16x32_bf16 v[2:5], v[184:187], v[240:243], v[2:5]
	s_setprio 0
	s_barrier
	s_add_i32 s63, 0, 0x18000
	v_add_u32_e32 v152, s63, v157
	s_add_i32 s64, 0, 0x1c000
	ds_read_b128 v[130:133], v152
	ds_read_b128 v[134:137], v152 offset:1024
	ds_read_b128 v[160:163], v152 offset:2048
	ds_read_b128 v[168:171], v152 offset:3072
	v_add_u32_e32 v152, s64, v157
	ds_read_b128 v[172:175], v152
	ds_read_b128 v[176:179], v152 offset:1024
	ds_read_b128 v[180:183], v152 offset:2048
	ds_read_b128 v[184:187], v152 offset:3072
	s_add_u32 s48, s48, 0x80000
	s_addc_u32 s49, s49, 0
	s_mov_b32 m0, s51
	ds_read_b128 v[188:191], v167 offset:32768
	ds_read_b128 v[192:195], v167 offset:33792
	ds_read_b128 v[196:199], v167 offset:34816
	ds_read_b128 v[200:203], v167 offset:35840
	ds_read_b128 v[204:207], v167 offset:36864
	ds_read_b128 v[216:219], v167 offset:37888
	ds_read_b128 v[220:223], v167 offset:38912
	ds_read_b128 v[240:243], v167 offset:39936
	global_load_lds_dwordx4 v142, s[48:49]
	s_mov_b32 m0, s52
	s_nop 0
	global_load_lds_dwordx4 v140, s[48:49]
	s_waitcnt vmcnt(8)
	s_waitcnt lgkmcnt(0)
	s_barrier
	s_setprio 1
	s_waitcnt lgkmcnt(0)
	v_mfma_f32_16x16x32_bf16 v[126:129], v[130:133], v[188:191], v[126:129]
	v_mfma_f32_16x16x32_bf16 v[122:125], v[160:163], v[188:191], v[122:125]
	v_mfma_f32_16x16x32_bf16 v[110:113], v[130:133], v[196:199], v[110:113]
	v_mfma_f32_16x16x32_bf16 v[106:109], v[160:163], v[196:199], v[106:109]
	v_mfma_f32_16x16x32_bf16 v[94:97], v[130:133], v[204:207], v[94:97]
	v_mfma_f32_16x16x32_bf16 v[90:93], v[160:163], v[204:207], v[90:93]
	v_mfma_f32_16x16x32_bf16 v[78:81], v[130:133], v[220:223], v[78:81]
	v_mfma_f32_16x16x32_bf16 v[74:77], v[160:163], v[220:223], v[74:77]
	v_mfma_f32_16x16x32_bf16 v[126:129], v[134:137], v[192:195], v[126:129]
	v_mfma_f32_16x16x32_bf16 v[122:125], v[168:171], v[192:195], v[122:125]
	v_mfma_f32_16x16x32_bf16 v[110:113], v[134:137], v[200:203], v[110:113]
	v_mfma_f32_16x16x32_bf16 v[106:109], v[168:171], v[200:203], v[106:109]
	v_mfma_f32_16x16x32_bf16 v[94:97], v[134:137], v[216:219], v[94:97]
	v_mfma_f32_16x16x32_bf16 v[90:93], v[168:171], v[216:219], v[90:93]
	v_mfma_f32_16x16x32_bf16 v[78:81], v[134:137], v[240:243], v[78:81]
	v_mfma_f32_16x16x32_bf16 v[74:77], v[168:171], v[240:243], v[74:77]
	s_setprio 0
	s_setprio 1
	v_mfma_f32_16x16x32_bf16 v[118:121], v[172:175], v[188:191], v[118:121]
	v_mfma_f32_16x16x32_bf16 v[114:117], v[180:183], v[188:191], v[114:117]
	v_mfma_f32_16x16x32_bf16 v[102:105], v[172:175], v[196:199], v[102:105]
	v_mfma_f32_16x16x32_bf16 v[98:101], v[180:183], v[196:199], v[98:101]
	v_mfma_f32_16x16x32_bf16 v[86:89], v[172:175], v[204:207], v[86:89]
	v_mfma_f32_16x16x32_bf16 v[82:85], v[180:183], v[204:207], v[82:85]
	v_mfma_f32_16x16x32_bf16 v[70:73], v[172:175], v[220:223], v[70:73]
	v_mfma_f32_16x16x32_bf16 v[66:69], v[180:183], v[220:223], v[66:69]
	v_mfma_f32_16x16x32_bf16 v[118:121], v[176:179], v[192:195], v[118:121]
	v_mfma_f32_16x16x32_bf16 v[114:117], v[184:187], v[192:195], v[114:117]
	v_mfma_f32_16x16x32_bf16 v[102:105], v[176:179], v[200:203], v[102:105]
	v_mfma_f32_16x16x32_bf16 v[98:101], v[184:187], v[200:203], v[98:101]
	v_mfma_f32_16x16x32_bf16 v[86:89], v[176:179], v[216:219], v[86:89]
	v_mfma_f32_16x16x32_bf16 v[82:85], v[184:187], v[216:219], v[82:85]
	v_mfma_f32_16x16x32_bf16 v[70:73], v[176:179], v[240:243], v[70:73]
	v_mfma_f32_16x16x32_bf16 v[66:69], v[184:187], v[240:243], v[66:69]
	s_setprio 0
	s_barrier
	s_add_i32 s48, s63, s19
	v_lshl_add_u64 v[150:151], v[150:151], 0, s[22:23]
	s_mov_b32 m0, s48
	ds_read_b128 v[188:191], v167 offset:49152
	ds_read_b128 v[192:195], v167 offset:50176
	ds_read_b128 v[196:199], v167 offset:51200
	ds_read_b128 v[200:203], v167 offset:52224
	ds_read_b128 v[204:207], v167 offset:53248
	ds_read_b128 v[216:219], v167 offset:54272
	ds_read_b128 v[220:223], v167 offset:55296
	ds_read_b128 v[240:243], v167 offset:56320
	global_load_lds_dwordx4 v[150:151], off
	s_add_i32 m0, s48, 0x2000
	s_add_u32 s46, s46, 0x80080
	v_lshl_add_u64 v[150:151], v[154:155], 0, s[22:23]
	s_addc_u32 s47, s47, 0
	s_add_i32 s48, s64, s19
	global_load_lds_dwordx4 v[150:151], off
	s_mov_b32 m0, s48
	s_nop 0
	global_load_lds_dwordx4 v0, s[46:47]
	s_add_i32 m0, s48, 0x2000
	s_nop 0
	global_load_lds_dwordx4 v138, s[46:47]
	v_lshl_add_u64 v[150:151], v[164:165], 0, s[22:23]
	s_mov_b32 m0, s53
	s_nop 0
	global_load_lds_dwordx4 v[150:151], off
	v_lshl_add_u64 v[150:151], v[208:209], 0, s[22:23]
	s_mov_b32 m0, s54
	s_nop 0
	global_load_lds_dwordx4 v[150:151], off
	s_waitcnt vmcnt(8)
	s_waitcnt lgkmcnt(0)
	s_barrier
	s_setprio 1
	s_waitcnt lgkmcnt(0)
	v_mfma_f32_16x16x32_bf16 v[62:65], v[130:133], v[188:191], v[62:65]
	v_mfma_f32_16x16x32_bf16 v[58:61], v[160:163], v[188:191], v[58:61]
	v_mfma_f32_16x16x32_bf16 v[46:49], v[130:133], v[196:199], v[46:49]
	v_mfma_f32_16x16x32_bf16 v[42:45], v[160:163], v[196:199], v[42:45]
	v_mfma_f32_16x16x32_bf16 v[30:33], v[130:133], v[204:207], v[30:33]
	v_mfma_f32_16x16x32_bf16 v[26:29], v[160:163], v[204:207], v[26:29]
	v_mfma_f32_16x16x32_bf16 v[14:17], v[130:133], v[220:223], v[14:17]
	v_mfma_f32_16x16x32_bf16 v[10:13], v[160:163], v[220:223], v[10:13]
	v_mfma_f32_16x16x32_bf16 v[62:65], v[134:137], v[192:195], v[62:65]
	v_mfma_f32_16x16x32_bf16 v[58:61], v[168:171], v[192:195], v[58:61]
	v_mfma_f32_16x16x32_bf16 v[46:49], v[134:137], v[200:203], v[46:49]
	v_mfma_f32_16x16x32_bf16 v[42:45], v[168:171], v[200:203], v[42:45]
	v_mfma_f32_16x16x32_bf16 v[30:33], v[134:137], v[216:219], v[30:33]
	v_mfma_f32_16x16x32_bf16 v[26:29], v[168:171], v[216:219], v[26:29]
	v_mfma_f32_16x16x32_bf16 v[14:17], v[134:137], v[240:243], v[14:17]
	v_mfma_f32_16x16x32_bf16 v[10:13], v[168:171], v[240:243], v[10:13]
	s_setprio 0
	s_setprio 1
	v_mfma_f32_16x16x32_bf16 v[54:57], v[172:175], v[188:191], v[54:57]
	v_mfma_f32_16x16x32_bf16 v[50:53], v[180:183], v[188:191], v[50:53]
	v_mfma_f32_16x16x32_bf16 v[38:41], v[172:175], v[196:199], v[38:41]
	v_mfma_f32_16x16x32_bf16 v[34:37], v[180:183], v[196:199], v[34:37]
	v_mfma_f32_16x16x32_bf16 v[22:25], v[172:175], v[204:207], v[22:25]
	v_mfma_f32_16x16x32_bf16 v[18:21], v[180:183], v[204:207], v[18:21]
	v_mfma_f32_16x16x32_bf16 v[6:9], v[172:175], v[220:223], v[6:9]
	v_mfma_f32_16x16x32_bf16 v[2:5], v[180:183], v[220:223], v[2:5]
	v_mfma_f32_16x16x32_bf16 v[54:57], v[176:179], v[192:195], v[54:57]
	v_mfma_f32_16x16x32_bf16 v[50:53], v[184:187], v[192:195], v[50:53]
	v_mfma_f32_16x16x32_bf16 v[38:41], v[176:179], v[200:203], v[38:41]
	v_mfma_f32_16x16x32_bf16 v[34:37], v[184:187], v[200:203], v[34:37]
	v_mfma_f32_16x16x32_bf16 v[22:25], v[176:179], v[216:219], v[22:25]
	v_mfma_f32_16x16x32_bf16 v[18:21], v[184:187], v[216:219], v[18:21]
	v_mfma_f32_16x16x32_bf16 v[6:9], v[176:179], v[240:243], v[6:9]
	v_mfma_f32_16x16x32_bf16 v[2:5], v[184:187], v[240:243], v[2:5]
	s_setprio 0
	s_barrier
	s_add_i32 s62, s62, 2
	s_add_u32 s0, s0, 0x100
	s_addc_u32 s1, s1, 0
	s_add_u32 s60, s60, 0x100
	s_addc_u32 s61, s61, 0
	s_cmp_gt_u32 s62, 29
	s_cbranch_scc0 .LBB0_1667
	s_and_b64 vcc, exec, s[30:31]
	s_cbranch_vccz .LBB0_1670
	s_barrier

.LBB0_1763:
	s_add_u32 s48, s46, 0xffe00080
	s_addc_u32 s49, s47, -1
	s_add_i32 s66, 0, 0x10000
	s_cmpk_eq_i32 s65, 0x7c
	s_cselect_b32 s51, s37, s49
	s_cselect_b32 s50, s61, s48
	s_cselect_b32 s49, s31, s64
	s_cselect_b32 s48, s62, s63
	s_add_i32 s68, 0, 0x14000
	v_add_u32_e32 v142, s66, v167
	v_add_u32_e32 v164, s68, v167
	ds_read_b128 v[130:133], v142
	ds_read_b128 v[134:137], v142 offset:1024
	ds_read_b128 v[138:141], v142 offset:2048
	ds_read_b128 v[142:145], v142 offset:3072
	ds_read_b128 v[156:159], v164
	ds_read_b128 v[160:163], v164 offset:1024
	ds_read_b128 v[170:173], v164 offset:2048
	ds_read_b128 v[174:177], v164 offset:3072
	s_add_i32 m0, s52, 0xc000
	ds_read_b128 v[178:181], v169
	ds_read_b128 v[182:185], v169 offset:1024
	ds_read_b128 v[186:189], v169 offset:2048
	ds_read_b128 v[190:193], v169 offset:3072
	ds_read_b128 v[194:197], v169 offset:4096
	ds_read_b128 v[198:201], v169 offset:5120
	ds_read_b128 v[202:205], v169 offset:6144
	ds_read_b128 v[206:209], v169 offset:7168
	global_load_lds_dwordx4 v152, s[46:47]
	s_add_i32 m0, s52, 0xe000
	s_nop 0
	global_load_lds_dwordx4 v154, s[46:47]
	s_waitcnt vmcnt(8)
	s_waitcnt lgkmcnt(0)
	s_barrier
	s_setprio 1
	s_waitcnt lgkmcnt(0)
	v_mfma_f32_16x16x32_bf16 v[126:129], v[130:133], v[178:181], v[126:129]
	v_mfma_f32_16x16x32_bf16 v[122:125], v[138:141], v[178:181], v[122:125]
	v_mfma_f32_16x16x32_bf16 v[110:113], v[130:133], v[186:189], v[110:113]
	v_mfma_f32_16x16x32_bf16 v[106:109], v[138:141], v[186:189], v[106:109]
	v_mfma_f32_16x16x32_bf16 v[94:97], v[130:133], v[194:197], v[94:97]
	v_mfma_f32_16x16x32_bf16 v[90:93], v[138:141], v[194:197], v[90:93]
	v_mfma_f32_16x16x32_bf16 v[78:81], v[130:133], v[202:205], v[78:81]
	v_mfma_f32_16x16x32_bf16 v[74:77], v[138:141], v[202:205], v[74:77]
	v_mfma_f32_16x16x32_bf16 v[126:129], v[134:137], v[182:185], v[126:129]
	v_mfma_f32_16x16x32_bf16 v[122:125], v[142:145], v[182:185], v[122:125]
	v_mfma_f32_16x16x32_bf16 v[110:113], v[134:137], v[190:193], v[110:113]
	v_mfma_f32_16x16x32_bf16 v[106:109], v[142:145], v[190:193], v[106:109]
	v_mfma_f32_16x16x32_bf16 v[94:97], v[134:137], v[198:201], v[94:97]
	v_mfma_f32_16x16x32_bf16 v[90:93], v[142:145], v[198:201], v[90:93]
	v_mfma_f32_16x16x32_bf16 v[78:81], v[134:137], v[206:209], v[78:81]
	v_mfma_f32_16x16x32_bf16 v[74:77], v[142:145], v[206:209], v[74:77]
	s_setprio 0
	s_setprio 1
	v_mfma_f32_16x16x32_bf16 v[118:121], v[156:159], v[178:181], v[118:121]
	v_mfma_f32_16x16x32_bf16 v[114:117], v[170:173], v[178:181], v[114:117]
	v_mfma_f32_16x16x32_bf16 v[102:105], v[156:159], v[186:189], v[102:105]
	v_mfma_f32_16x16x32_bf16 v[98:101], v[170:173], v[186:189], v[98:101]
	v_mfma_f32_16x16x32_bf16 v[86:89], v[156:159], v[194:197], v[86:89]
	v_mfma_f32_16x16x32_bf16 v[82:85], v[170:173], v[194:197], v[82:85]
	v_mfma_f32_16x16x32_bf16 v[70:73], v[156:159], v[202:205], v[70:73]
	v_mfma_f32_16x16x32_bf16 v[66:69], v[170:173], v[202:205], v[66:69]
	v_mfma_f32_16x16x32_bf16 v[118:121], v[160:163], v[182:185], v[118:121]
	v_mfma_f32_16x16x32_bf16 v[114:117], v[174:177], v[182:185], v[114:117]
	v_mfma_f32_16x16x32_bf16 v[102:105], v[160:163], v[190:193], v[102:105]
	v_mfma_f32_16x16x32_bf16 v[98:101], v[174:177], v[190:193], v[98:101]
	v_mfma_f32_16x16x32_bf16 v[86:89], v[160:163], v[198:201], v[86:89]
	v_mfma_f32_16x16x32_bf16 v[82:85], v[174:177], v[198:201], v[82:85]
	v_mfma_f32_16x16x32_bf16 v[70:73], v[160:163], v[206:209], v[70:73]
	v_mfma_f32_16x16x32_bf16 v[66:69], v[174:177], v[206:209], v[66:69]
	s_setprio 0
	s_barrier
	s_add_i32 s66, s66, s19
	v_lshl_add_u64 v[164:165], s[48:49], 0, v[0:1]
	s_mov_b32 m0, s66
	ds_read_b128 v[178:181], v169 offset:16384
	ds_read_b128 v[182:185], v169 offset:17408
	ds_read_b128 v[186:189], v169 offset:18432
	ds_read_b128 v[190:193], v169 offset:19456
	ds_read_b128 v[194:197], v169 offset:20480
	ds_read_b128 v[198:201], v169 offset:21504
	ds_read_b128 v[202:205], v169 offset:22528
	ds_read_b128 v[206:209], v169 offset:23552
	global_load_lds_dwordx4 v0, s[48:49]
	s_add_i32 m0, s66, 0x2000
	s_add_u32 s66, s48, 0x200000
	v_lshl_add_u64 v[216:217], s[48:49], 0, v[146:147]
	s_addc_u32 s67, s49, 0
	s_add_i32 s68, s68, s19
	global_load_lds_dwordx4 v146, s[48:49]
	s_mov_b32 m0, s68
	v_lshl_add_u64 v[220:221], s[50:51], 0, v[148:149]
	global_load_lds_dwordx4 v0, s[66:67]
	s_add_i32 m0, s68, 0x2000
	s_nop 0
	global_load_lds_dwordx4 v146, s[66:67]
	v_lshl_add_u64 v[218:219], s[50:51], 0, v[150:151]
	s_mov_b32 m0, s52
	s_nop 0
	global_load_lds_dwordx4 v150, s[50:51]
	s_mov_b32 m0, s53
	s_nop 0
	global_load_lds_dwordx4 v148, s[50:51]
	s_waitcnt vmcnt(8)
	s_waitcnt lgkmcnt(0)
	s_barrier
	s_setprio 1
	s_waitcnt lgkmcnt(0)
	v_mfma_f32_16x16x32_bf16 v[62:65], v[130:133], v[178:181], v[62:65]
	v_mfma_f32_16x16x32_bf16 v[58:61], v[138:141], v[178:181], v[58:61]
	v_mfma_f32_16x16x32_bf16 v[46:49], v[130:133], v[186:189], v[46:49]
	v_mfma_f32_16x16x32_bf16 v[42:45], v[138:141], v[186:189], v[42:45]
	v_mfma_f32_16x16x32_bf16 v[30:33], v[130:133], v[194:197], v[30:33]
	v_mfma_f32_16x16x32_bf16 v[26:29], v[138:141], v[194:197], v[26:29]
	v_mfma_f32_16x16x32_bf16 v[14:17], v[130:133], v[202:205], v[14:17]
	v_mfma_f32_16x16x32_bf16 v[10:13], v[138:141], v[202:205], v[10:13]
	v_mfma_f32_16x16x32_bf16 v[62:65], v[134:137], v[182:185], v[62:65]
	v_mfma_f32_16x16x32_bf16 v[58:61], v[142:145], v[182:185], v[58:61]
	v_mfma_f32_16x16x32_bf16 v[46:49], v[134:137], v[190:193], v[46:49]
	v_mfma_f32_16x16x32_bf16 v[42:45], v[142:145], v[190:193], v[42:45]
	v_mfma_f32_16x16x32_bf16 v[30:33], v[134:137], v[198:201], v[30:33]
	v_mfma_f32_16x16x32_bf16 v[26:29], v[142:145], v[198:201], v[26:29]
	v_mfma_f32_16x16x32_bf16 v[14:17], v[134:137], v[206:209], v[14:17]
	v_mfma_f32_16x16x32_bf16 v[10:13], v[142:145], v[206:209], v[10:13]
	s_setprio 0
	s_setprio 1
	v_mfma_f32_16x16x32_bf16 v[54:57], v[156:159], v[178:181], v[54:57]
	v_mfma_f32_16x16x32_bf16 v[50:53], v[170:173], v[178:181], v[50:53]
	v_mfma_f32_16x16x32_bf16 v[38:41], v[156:159], v[186:189], v[38:41]
	v_mfma_f32_16x16x32_bf16 v[34:37], v[170:173], v[186:189], v[34:37]
	v_mfma_f32_16x16x32_bf16 v[22:25], v[156:159], v[194:197], v[22:25]
	v_mfma_f32_16x16x32_bf16 v[18:21], v[170:173], v[194:197], v[18:21]
	v_mfma_f32_16x16x32_bf16 v[6:9], v[156:159], v[202:205], v[6:9]
	v_mfma_f32_16x16x32_bf16 v[2:5], v[170:173], v[202:205], v[2:5]
	v_mfma_f32_16x16x32_bf16 v[54:57], v[160:163], v[182:185], v[54:57]
	v_mfma_f32_16x16x32_bf16 v[50:53], v[174:177], v[182:185], v[50:53]
	v_mfma_f32_16x16x32_bf16 v[38:41], v[160:163], v[190:193], v[38:41]
	v_mfma_f32_16x16x32_bf16 v[34:37], v[174:177], v[190:193], v[34:37]
	v_mfma_f32_16x16x32_bf16 v[22:25], v[160:163], v[198:201], v[22:25]
	v_mfma_f32_16x16x32_bf16 v[18:21], v[174:177], v[198:201], v[18:21]
	v_mfma_f32_16x16x32_bf16 v[6:9], v[160:163], v[206:209], v[6:9]
	v_mfma_f32_16x16x32_bf16 v[2:5], v[174:177], v[206:209], v[2:5]
	s_setprio 0
	s_barrier
	s_add_i32 s66, 0, 0x18000
	s_add_i32 s67, 0, 0x1c000
	v_add_u32_e32 v142, s66, v167
	v_add_u32_e32 v174, s67, v167
	ds_read_b128 v[130:133], v142
	ds_read_b128 v[134:137], v142 offset:1024
	ds_read_b128 v[138:141], v142 offset:2048
	ds_read_b128 v[142:145], v142 offset:3072
	ds_read_b128 v[156:159], v174
	ds_read_b128 v[160:163], v174 offset:1024
	ds_read_b128 v[170:173], v174 offset:2048
	ds_read_b128 v[174:177], v174 offset:3072
	s_add_u32 s50, s50, 0x200000
	s_addc_u32 s51, s51, 0
	s_mov_b32 m0, s54
	ds_read_b128 v[178:181], v169 offset:32768
	ds_read_b128 v[182:185], v169 offset:33792
	ds_read_b128 v[186:189], v169 offset:34816
	ds_read_b128 v[190:193], v169 offset:35840
	ds_read_b128 v[194:197], v169 offset:36864
	ds_read_b128 v[198:201], v169 offset:37888
	ds_read_b128 v[202:205], v169 offset:38912
	ds_read_b128 v[206:209], v169 offset:39936
	global_load_lds_dwordx4 v150, s[50:51]
	s_mov_b32 m0, s55
	s_nop 0
	global_load_lds_dwordx4 v148, s[50:51]
	s_waitcnt vmcnt(8)
	s_waitcnt lgkmcnt(0)
	s_barrier
	s_setprio 1
	s_waitcnt lgkmcnt(0)
	v_mfma_f32_16x16x32_bf16 v[126:129], v[130:133], v[178:181], v[126:129]
	v_mfma_f32_16x16x32_bf16 v[122:125], v[138:141], v[178:181], v[122:125]
	v_mfma_f32_16x16x32_bf16 v[110:113], v[130:133], v[186:189], v[110:113]
	v_mfma_f32_16x16x32_bf16 v[106:109], v[138:141], v[186:189], v[106:109]
	v_mfma_f32_16x16x32_bf16 v[94:97], v[130:133], v[194:197], v[94:97]
	v_mfma_f32_16x16x32_bf16 v[90:93], v[138:141], v[194:197], v[90:93]
	v_mfma_f32_16x16x32_bf16 v[78:81], v[130:133], v[202:205], v[78:81]
	v_mfma_f32_16x16x32_bf16 v[74:77], v[138:141], v[202:205], v[74:77]
	v_mfma_f32_16x16x32_bf16 v[126:129], v[134:137], v[182:185], v[126:129]
	v_mfma_f32_16x16x32_bf16 v[122:125], v[142:145], v[182:185], v[122:125]
	v_mfma_f32_16x16x32_bf16 v[110:113], v[134:137], v[190:193], v[110:113]
	v_mfma_f32_16x16x32_bf16 v[106:109], v[142:145], v[190:193], v[106:109]
	v_mfma_f32_16x16x32_bf16 v[94:97], v[134:137], v[198:201], v[94:97]
	v_mfma_f32_16x16x32_bf16 v[90:93], v[142:145], v[198:201], v[90:93]
	v_mfma_f32_16x16x32_bf16 v[78:81], v[134:137], v[206:209], v[78:81]
	v_mfma_f32_16x16x32_bf16 v[74:77], v[142:145], v[206:209], v[74:77]
	s_setprio 0
	s_setprio 1
	v_mfma_f32_16x16x32_bf16 v[118:121], v[156:159], v[178:181], v[118:121]
	v_mfma_f32_16x16x32_bf16 v[114:117], v[170:173], v[178:181], v[114:117]
	v_mfma_f32_16x16x32_bf16 v[102:105], v[156:159], v[186:189], v[102:105]
	v_mfma_f32_16x16x32_bf16 v[98:101], v[170:173], v[186:189], v[98:101]
	v_mfma_f32_16x16x32_bf16 v[86:89], v[156:159], v[194:197], v[86:89]
	v_mfma_f32_16x16x32_bf16 v[82:85], v[170:173], v[194:197], v[82:85]
	v_mfma_f32_16x16x32_bf16 v[70:73], v[156:159], v[202:205], v[70:73]
	v_mfma_f32_16x16x32_bf16 v[66:69], v[170:173], v[202:205], v[66:69]
	v_mfma_f32_16x16x32_bf16 v[118:121], v[160:163], v[182:185], v[118:121]
	v_mfma_f32_16x16x32_bf16 v[114:117], v[174:177], v[182:185], v[114:117]
	v_mfma_f32_16x16x32_bf16 v[102:105], v[160:163], v[190:193], v[102:105]
	v_mfma_f32_16x16x32_bf16 v[98:101], v[174:177], v[190:193], v[98:101]
	v_mfma_f32_16x16x32_bf16 v[86:89], v[160:163], v[198:201], v[86:89]
	v_mfma_f32_16x16x32_bf16 v[82:85], v[174:177], v[198:201], v[82:85]
	v_mfma_f32_16x16x32_bf16 v[70:73], v[160:163], v[206:209], v[70:73]
	v_mfma_f32_16x16x32_bf16 v[66:69], v[174:177], v[206:209], v[66:69]
	s_setprio 0
	s_barrier
	s_add_i32 s50, s66, s19
	v_lshl_add_u64 v[164:165], v[164:165], 0, s[22:23]
	s_mov_b32 m0, s50
	ds_read_b128 v[178:181], v169 offset:49152
	ds_read_b128 v[182:185], v169 offset:50176
	ds_read_b128 v[186:189], v169 offset:51200
	ds_read_b128 v[190:193], v169 offset:52224
	ds_read_b128 v[194:197], v169 offset:53248
	ds_read_b128 v[198:201], v169 offset:54272
	ds_read_b128 v[202:205], v169 offset:55296
	ds_read_b128 v[206:209], v169 offset:56320
	global_load_lds_dwordx4 v[164:165], off
	s_add_i32 m0, s50, 0x2000
	s_add_u32 s48, s48, 0x200080
	v_lshl_add_u64 v[164:165], v[216:217], 0, s[22:23]
	s_addc_u32 s49, s49, 0
	s_add_i32 s50, s67, s19
	global_load_lds_dwordx4 v[164:165], off
	s_mov_b32 m0, s50
	s_nop 0
	global_load_lds_dwordx4 v0, s[48:49]
	s_add_i32 m0, s50, 0x2000
	s_nop 0
	global_load_lds_dwordx4 v146, s[48:49]
	v_lshl_add_u64 v[164:165], v[218:219], 0, s[22:23]
	s_mov_b32 m0, s57
	s_nop 0
	global_load_lds_dwordx4 v[164:165], off
	v_lshl_add_u64 v[164:165], v[220:221], 0, s[22:23]
	s_mov_b32 m0, s58
	s_nop 0
	global_load_lds_dwordx4 v[164:165], off
	s_waitcnt vmcnt(8)
	s_waitcnt lgkmcnt(0)
	s_barrier
	s_setprio 1
	s_waitcnt lgkmcnt(0)
	v_mfma_f32_16x16x32_bf16 v[62:65], v[130:133], v[178:181], v[62:65]
	v_mfma_f32_16x16x32_bf16 v[58:61], v[138:141], v[178:181], v[58:61]
	v_mfma_f32_16x16x32_bf16 v[46:49], v[130:133], v[186:189], v[46:49]
	v_mfma_f32_16x16x32_bf16 v[42:45], v[138:141], v[186:189], v[42:45]
	v_mfma_f32_16x16x32_bf16 v[30:33], v[130:133], v[194:197], v[30:33]
	v_mfma_f32_16x16x32_bf16 v[26:29], v[138:141], v[194:197], v[26:29]
	v_mfma_f32_16x16x32_bf16 v[14:17], v[130:133], v[202:205], v[14:17]
	v_mfma_f32_16x16x32_bf16 v[10:13], v[138:141], v[202:205], v[10:13]
	v_mfma_f32_16x16x32_bf16 v[62:65], v[134:137], v[182:185], v[62:65]
	v_mfma_f32_16x16x32_bf16 v[58:61], v[142:145], v[182:185], v[58:61]
	v_mfma_f32_16x16x32_bf16 v[46:49], v[134:137], v[190:193], v[46:49]
	v_mfma_f32_16x16x32_bf16 v[42:45], v[142:145], v[190:193], v[42:45]
	v_mfma_f32_16x16x32_bf16 v[30:33], v[134:137], v[198:201], v[30:33]
	v_mfma_f32_16x16x32_bf16 v[26:29], v[142:145], v[198:201], v[26:29]
	v_mfma_f32_16x16x32_bf16 v[14:17], v[134:137], v[206:209], v[14:17]
	v_mfma_f32_16x16x32_bf16 v[10:13], v[142:145], v[206:209], v[10:13]
	s_setprio 0
	s_setprio 1
	v_mfma_f32_16x16x32_bf16 v[54:57], v[156:159], v[178:181], v[54:57]
	v_mfma_f32_16x16x32_bf16 v[50:53], v[170:173], v[178:181], v[50:53]
	v_mfma_f32_16x16x32_bf16 v[38:41], v[156:159], v[186:189], v[38:41]
	v_mfma_f32_16x16x32_bf16 v[34:37], v[170:173], v[186:189], v[34:37]
	v_mfma_f32_16x16x32_bf16 v[22:25], v[156:159], v[194:197], v[22:25]
	v_mfma_f32_16x16x32_bf16 v[18:21], v[170:173], v[194:197], v[18:21]
	v_mfma_f32_16x16x32_bf16 v[6:9], v[156:159], v[202:205], v[6:9]
	v_mfma_f32_16x16x32_bf16 v[2:5], v[170:173], v[202:205], v[2:5]
	v_mfma_f32_16x16x32_bf16 v[54:57], v[160:163], v[182:185], v[54:57]
	v_mfma_f32_16x16x32_bf16 v[50:53], v[174:177], v[182:185], v[50:53]
	v_mfma_f32_16x16x32_bf16 v[38:41], v[160:163], v[190:193], v[38:41]
	v_mfma_f32_16x16x32_bf16 v[34:37], v[174:177], v[190:193], v[34:37]
	v_mfma_f32_16x16x32_bf16 v[22:25], v[160:163], v[198:201], v[22:25]
	v_mfma_f32_16x16x32_bf16 v[18:21], v[174:177], v[198:201], v[18:21]
	v_mfma_f32_16x16x32_bf16 v[6:9], v[160:163], v[206:209], v[6:9]
	v_mfma_f32_16x16x32_bf16 v[2:5], v[174:177], v[206:209], v[2:5]
	s_setprio 0
	s_barrier
	s_add_i32 s65, s65, 2
	s_add_u32 s46, s46, 0x100
	s_addc_u32 s47, s47, 0
	s_add_u32 s63, s63, 0x100
	s_addc_u32 s64, s64, 0
	s_cmpk_gt_u32 s65, 0x7d
	s_cbranch_scc0 .LBB0_1763
	s_and_b64 vcc, exec, s[8:9]
	s_cbranch_vccz .LBB0_1766
	s_barrier

.LBB0_1855:
	s_add_u32 s30, s2, 0xfff80080
	s_addc_u32 s31, s3, -1
	s_add_i32 s68, 0, 0x10000
	s_cmp_eq_u32 s67, 28
	s_cselect_b32 s43, s49, s31
	s_cselect_b32 s42, s55, s30
	s_cselect_b32 s31, s37, s66
	s_cselect_b32 s30, s64, s65
	s_add_i32 s70, 0, 0x14000
	v_add_u32_e32 v142, s68, v241
	v_add_u32_e32 v170, s70, v241
	ds_read_b128 v[130:133], v142
	ds_read_b128 v[134:137], v142 offset:1024
	ds_read_b128 v[138:141], v142 offset:2048
	ds_read_b128 v[142:145], v142 offset:3072
	ds_read_b128 v[146:149], v170
	ds_read_b128 v[150:153], v170 offset:1024
	ds_read_b128 v[166:169], v170 offset:2048
	ds_read_b128 v[170:173], v170 offset:3072
	s_add_i32 m0, s56, 0xc000
	ds_read_b128 v[174:177], v243
	ds_read_b128 v[178:181], v243 offset:1024
	ds_read_b128 v[182:185], v243 offset:2048
	ds_read_b128 v[186:189], v243 offset:3072
	ds_read_b128 v[190:193], v243 offset:4096
	ds_read_b128 v[194:197], v243 offset:5120
	ds_read_b128 v[198:201], v243 offset:6144
	ds_read_b128 v[202:205], v243 offset:7168
	global_load_lds_dwordx4 v162, s[2:3]
	s_add_i32 m0, s56, 0xe000
	s_nop 0
	global_load_lds_dwordx4 v164, s[2:3]
	s_waitcnt vmcnt(8)
	s_waitcnt lgkmcnt(0)
	s_barrier
	s_setprio 1
	s_waitcnt lgkmcnt(0)
	v_mfma_f32_16x16x32_bf16 v[126:129], v[130:133], v[174:177], v[126:129]
	v_mfma_f32_16x16x32_bf16 v[122:125], v[138:141], v[174:177], v[122:125]
	v_mfma_f32_16x16x32_bf16 v[110:113], v[130:133], v[182:185], v[110:113]
	v_mfma_f32_16x16x32_bf16 v[106:109], v[138:141], v[182:185], v[106:109]
	v_mfma_f32_16x16x32_bf16 v[94:97], v[130:133], v[190:193], v[94:97]
	v_mfma_f32_16x16x32_bf16 v[90:93], v[138:141], v[190:193], v[90:93]
	v_mfma_f32_16x16x32_bf16 v[78:81], v[130:133], v[198:201], v[78:81]
	v_mfma_f32_16x16x32_bf16 v[74:77], v[138:141], v[198:201], v[74:77]
	v_mfma_f32_16x16x32_bf16 v[126:129], v[134:137], v[178:181], v[126:129]
	v_mfma_f32_16x16x32_bf16 v[122:125], v[142:145], v[178:181], v[122:125]
	v_mfma_f32_16x16x32_bf16 v[110:113], v[134:137], v[186:189], v[110:113]
	v_mfma_f32_16x16x32_bf16 v[106:109], v[142:145], v[186:189], v[106:109]
	v_mfma_f32_16x16x32_bf16 v[94:97], v[134:137], v[194:197], v[94:97]
	v_mfma_f32_16x16x32_bf16 v[90:93], v[142:145], v[194:197], v[90:93]
	v_mfma_f32_16x16x32_bf16 v[78:81], v[134:137], v[202:205], v[78:81]
	v_mfma_f32_16x16x32_bf16 v[74:77], v[142:145], v[202:205], v[74:77]
	s_setprio 0
	s_setprio 1
	v_mfma_f32_16x16x32_bf16 v[118:121], v[146:149], v[174:177], v[118:121]
	v_mfma_f32_16x16x32_bf16 v[114:117], v[166:169], v[174:177], v[114:117]
	v_mfma_f32_16x16x32_bf16 v[102:105], v[146:149], v[182:185], v[102:105]
	v_mfma_f32_16x16x32_bf16 v[98:101], v[166:169], v[182:185], v[98:101]
	v_mfma_f32_16x16x32_bf16 v[86:89], v[146:149], v[190:193], v[86:89]
	v_mfma_f32_16x16x32_bf16 v[82:85], v[166:169], v[190:193], v[82:85]
	v_mfma_f32_16x16x32_bf16 v[70:73], v[146:149], v[198:201], v[70:73]
	v_mfma_f32_16x16x32_bf16 v[66:69], v[166:169], v[198:201], v[66:69]
	v_mfma_f32_16x16x32_bf16 v[118:121], v[150:153], v[178:181], v[118:121]
	v_mfma_f32_16x16x32_bf16 v[114:117], v[170:173], v[178:181], v[114:117]
	v_mfma_f32_16x16x32_bf16 v[102:105], v[150:153], v[186:189], v[102:105]
	v_mfma_f32_16x16x32_bf16 v[98:101], v[170:173], v[186:189], v[98:101]
	v_mfma_f32_16x16x32_bf16 v[86:89], v[150:153], v[194:197], v[86:89]
	v_mfma_f32_16x16x32_bf16 v[82:85], v[170:173], v[194:197], v[82:85]
	v_mfma_f32_16x16x32_bf16 v[70:73], v[150:153], v[202:205], v[70:73]
	v_mfma_f32_16x16x32_bf16 v[66:69], v[170:173], v[202:205], v[66:69]
	s_setprio 0
	s_barrier
	s_add_i32 s68, s68, s19
	v_lshl_add_u64 v[206:207], s[30:31], 0, v[0:1]
	s_mov_b32 m0, s68
	ds_read_b128 v[174:177], v243 offset:16384
	ds_read_b128 v[178:181], v243 offset:17408
	ds_read_b128 v[182:185], v243 offset:18432
	ds_read_b128 v[186:189], v243 offset:19456
	ds_read_b128 v[190:193], v243 offset:20480
	ds_read_b128 v[194:197], v243 offset:21504
	ds_read_b128 v[198:201], v243 offset:22528
	ds_read_b128 v[202:205], v243 offset:23552
	global_load_lds_dwordx4 v0, s[30:31]
	s_add_i32 m0, s68, 0x2000
	s_add_u32 s68, s30, 0x80000
	v_lshl_add_u64 v[208:209], s[30:31], 0, v[154:155]
	s_addc_u32 s69, s31, 0
	s_add_i32 s70, s70, s19
	global_load_lds_dwordx4 v154, s[30:31]
	s_mov_b32 m0, s70
	v_lshl_add_u64 v[218:219], s[42:43], 0, v[156:157]
	global_load_lds_dwordx4 v0, s[68:69]
	s_add_i32 m0, s70, 0x2000
	s_nop 0
	global_load_lds_dwordx4 v154, s[68:69]
	v_lshl_add_u64 v[216:217], s[42:43], 0, v[158:159]
	s_mov_b32 m0, s56
	s_nop 0
	global_load_lds_dwordx4 v158, s[42:43]
	s_mov_b32 m0, s57
	s_nop 0
	global_load_lds_dwordx4 v156, s[42:43]
	s_waitcnt vmcnt(8)
	s_waitcnt lgkmcnt(0)
	s_barrier
	s_setprio 1
	s_waitcnt lgkmcnt(0)
	v_mfma_f32_16x16x32_bf16 v[62:65], v[130:133], v[174:177], v[62:65]
	v_mfma_f32_16x16x32_bf16 v[58:61], v[138:141], v[174:177], v[58:61]
	v_mfma_f32_16x16x32_bf16 v[46:49], v[130:133], v[182:185], v[46:49]
	v_mfma_f32_16x16x32_bf16 v[42:45], v[138:141], v[182:185], v[42:45]
	v_mfma_f32_16x16x32_bf16 v[30:33], v[130:133], v[190:193], v[30:33]
	v_mfma_f32_16x16x32_bf16 v[26:29], v[138:141], v[190:193], v[26:29]
	v_mfma_f32_16x16x32_bf16 v[14:17], v[130:133], v[198:201], v[14:17]
	v_mfma_f32_16x16x32_bf16 v[10:13], v[138:141], v[198:201], v[10:13]
	v_mfma_f32_16x16x32_bf16 v[62:65], v[134:137], v[178:181], v[62:65]
	v_mfma_f32_16x16x32_bf16 v[58:61], v[142:145], v[178:181], v[58:61]
	v_mfma_f32_16x16x32_bf16 v[46:49], v[134:137], v[186:189], v[46:49]
	v_mfma_f32_16x16x32_bf16 v[42:45], v[142:145], v[186:189], v[42:45]
	v_mfma_f32_16x16x32_bf16 v[30:33], v[134:137], v[194:197], v[30:33]
	v_mfma_f32_16x16x32_bf16 v[26:29], v[142:145], v[194:197], v[26:29]
	v_mfma_f32_16x16x32_bf16 v[14:17], v[134:137], v[202:205], v[14:17]
	v_mfma_f32_16x16x32_bf16 v[10:13], v[142:145], v[202:205], v[10:13]
	s_setprio 0
	s_setprio 1
	v_mfma_f32_16x16x32_bf16 v[54:57], v[146:149], v[174:177], v[54:57]
	v_mfma_f32_16x16x32_bf16 v[50:53], v[166:169], v[174:177], v[50:53]
	v_mfma_f32_16x16x32_bf16 v[38:41], v[146:149], v[182:185], v[38:41]
	v_mfma_f32_16x16x32_bf16 v[34:37], v[166:169], v[182:185], v[34:37]
	v_mfma_f32_16x16x32_bf16 v[22:25], v[146:149], v[190:193], v[22:25]
	v_mfma_f32_16x16x32_bf16 v[18:21], v[166:169], v[190:193], v[18:21]
	v_mfma_f32_16x16x32_bf16 v[6:9], v[146:149], v[198:201], v[6:9]
	v_mfma_f32_16x16x32_bf16 v[2:5], v[166:169], v[198:201], v[2:5]
	v_mfma_f32_16x16x32_bf16 v[54:57], v[150:153], v[178:181], v[54:57]
	v_mfma_f32_16x16x32_bf16 v[50:53], v[170:173], v[178:181], v[50:53]
	v_mfma_f32_16x16x32_bf16 v[38:41], v[150:153], v[186:189], v[38:41]
	v_mfma_f32_16x16x32_bf16 v[34:37], v[170:173], v[186:189], v[34:37]
	v_mfma_f32_16x16x32_bf16 v[22:25], v[150:153], v[194:197], v[22:25]
	v_mfma_f32_16x16x32_bf16 v[18:21], v[170:173], v[194:197], v[18:21]
	v_mfma_f32_16x16x32_bf16 v[6:9], v[150:153], v[202:205], v[6:9]
	v_mfma_f32_16x16x32_bf16 v[2:5], v[170:173], v[202:205], v[2:5]
	s_setprio 0
	s_barrier
	s_add_i32 s68, 0, 0x18000
	s_add_i32 s69, 0, 0x1c000
	v_add_u32_e32 v142, s68, v241
	v_add_u32_e32 v170, s69, v241
	ds_read_b128 v[130:133], v142
	ds_read_b128 v[134:137], v142 offset:1024
	ds_read_b128 v[138:141], v142 offset:2048
	ds_read_b128 v[142:145], v142 offset:3072
	ds_read_b128 v[146:149], v170
	ds_read_b128 v[150:153], v170 offset:1024
	ds_read_b128 v[166:169], v170 offset:2048
	ds_read_b128 v[170:173], v170 offset:3072
	s_add_u32 s42, s42, 0x80000
	s_addc_u32 s43, s43, 0
	s_mov_b32 m0, s58
	ds_read_b128 v[174:177], v243 offset:32768
	ds_read_b128 v[178:181], v243 offset:33792
	ds_read_b128 v[182:185], v243 offset:34816
	ds_read_b128 v[186:189], v243 offset:35840
	ds_read_b128 v[190:193], v243 offset:36864
	ds_read_b128 v[194:197], v243 offset:37888
	ds_read_b128 v[198:201], v243 offset:38912
	ds_read_b128 v[202:205], v243 offset:39936
	global_load_lds_dwordx4 v158, s[42:43]
	s_mov_b32 m0, s59
	s_nop 0
	global_load_lds_dwordx4 v156, s[42:43]
	s_waitcnt vmcnt(8)
	s_waitcnt lgkmcnt(0)
	s_barrier
	s_setprio 1
	s_waitcnt lgkmcnt(0)
	v_mfma_f32_16x16x32_bf16 v[126:129], v[130:133], v[174:177], v[126:129]
	v_mfma_f32_16x16x32_bf16 v[122:125], v[138:141], v[174:177], v[122:125]
	v_mfma_f32_16x16x32_bf16 v[110:113], v[130:133], v[182:185], v[110:113]
	v_mfma_f32_16x16x32_bf16 v[106:109], v[138:141], v[182:185], v[106:109]
	v_mfma_f32_16x16x32_bf16 v[94:97], v[130:133], v[190:193], v[94:97]
	v_mfma_f32_16x16x32_bf16 v[90:93], v[138:141], v[190:193], v[90:93]
	v_mfma_f32_16x16x32_bf16 v[78:81], v[130:133], v[198:201], v[78:81]
	v_mfma_f32_16x16x32_bf16 v[74:77], v[138:141], v[198:201], v[74:77]
	v_mfma_f32_16x16x32_bf16 v[126:129], v[134:137], v[178:181], v[126:129]
	v_mfma_f32_16x16x32_bf16 v[122:125], v[142:145], v[178:181], v[122:125]
	v_mfma_f32_16x16x32_bf16 v[110:113], v[134:137], v[186:189], v[110:113]
	v_mfma_f32_16x16x32_bf16 v[106:109], v[142:145], v[186:189], v[106:109]
	v_mfma_f32_16x16x32_bf16 v[94:97], v[134:137], v[194:197], v[94:97]
	v_mfma_f32_16x16x32_bf16 v[90:93], v[142:145], v[194:197], v[90:93]
	v_mfma_f32_16x16x32_bf16 v[78:81], v[134:137], v[202:205], v[78:81]
	v_mfma_f32_16x16x32_bf16 v[74:77], v[142:145], v[202:205], v[74:77]
	s_setprio 0
	s_setprio 1
	v_mfma_f32_16x16x32_bf16 v[118:121], v[146:149], v[174:177], v[118:121]
	v_mfma_f32_16x16x32_bf16 v[114:117], v[166:169], v[174:177], v[114:117]
	v_mfma_f32_16x16x32_bf16 v[102:105], v[146:149], v[182:185], v[102:105]
	v_mfma_f32_16x16x32_bf16 v[98:101], v[166:169], v[182:185], v[98:101]
	v_mfma_f32_16x16x32_bf16 v[86:89], v[146:149], v[190:193], v[86:89]
	v_mfma_f32_16x16x32_bf16 v[82:85], v[166:169], v[190:193], v[82:85]
	v_mfma_f32_16x16x32_bf16 v[70:73], v[146:149], v[198:201], v[70:73]
	v_mfma_f32_16x16x32_bf16 v[66:69], v[166:169], v[198:201], v[66:69]
	v_mfma_f32_16x16x32_bf16 v[118:121], v[150:153], v[178:181], v[118:121]
	v_mfma_f32_16x16x32_bf16 v[114:117], v[170:173], v[178:181], v[114:117]
	v_mfma_f32_16x16x32_bf16 v[102:105], v[150:153], v[186:189], v[102:105]
	v_mfma_f32_16x16x32_bf16 v[98:101], v[170:173], v[186:189], v[98:101]
	v_mfma_f32_16x16x32_bf16 v[86:89], v[150:153], v[194:197], v[86:89]
	v_mfma_f32_16x16x32_bf16 v[82:85], v[170:173], v[194:197], v[82:85]
	v_mfma_f32_16x16x32_bf16 v[70:73], v[150:153], v[202:205], v[70:73]
	v_mfma_f32_16x16x32_bf16 v[66:69], v[170:173], v[202:205], v[66:69]
	s_setprio 0
	s_barrier
	s_add_i32 s42, s68, s19
	v_lshl_add_u64 v[206:207], v[206:207], 0, s[22:23]
	s_mov_b32 m0, s42
	ds_read_b128 v[174:177], v243 offset:49152
	ds_read_b128 v[178:181], v243 offset:50176
	ds_read_b128 v[182:185], v243 offset:51200
	ds_read_b128 v[186:189], v243 offset:52224
	ds_read_b128 v[190:193], v243 offset:53248
	ds_read_b128 v[194:197], v243 offset:54272
	ds_read_b128 v[198:201], v243 offset:55296
	ds_read_b128 v[202:205], v243 offset:56320
	global_load_lds_dwordx4 v[206:207], off
	s_add_i32 m0, s42, 0x2000
	s_add_u32 s30, s30, 0x80080
	v_lshl_add_u64 v[206:207], v[208:209], 0, s[22:23]
	s_addc_u32 s31, s31, 0
	s_add_i32 s42, s69, s19
	global_load_lds_dwordx4 v[206:207], off
	s_mov_b32 m0, s42
	s_nop 0
	global_load_lds_dwordx4 v0, s[30:31]
	s_add_i32 m0, s42, 0x2000
	s_nop 0
	global_load_lds_dwordx4 v154, s[30:31]
	v_lshl_add_u64 v[206:207], v[216:217], 0, s[22:23]
	s_mov_b32 m0, s61
	s_nop 0
	global_load_lds_dwordx4 v[206:207], off
	v_lshl_add_u64 v[206:207], v[218:219], 0, s[22:23]
	s_mov_b32 m0, s62
	s_nop 0
	global_load_lds_dwordx4 v[206:207], off
	s_waitcnt vmcnt(8)
	s_waitcnt lgkmcnt(0)
	s_barrier
	s_setprio 1
	s_waitcnt lgkmcnt(0)
	v_mfma_f32_16x16x32_bf16 v[62:65], v[130:133], v[174:177], v[62:65]
	v_mfma_f32_16x16x32_bf16 v[58:61], v[138:141], v[174:177], v[58:61]
	v_mfma_f32_16x16x32_bf16 v[46:49], v[130:133], v[182:185], v[46:49]
	v_mfma_f32_16x16x32_bf16 v[42:45], v[138:141], v[182:185], v[42:45]
	v_mfma_f32_16x16x32_bf16 v[30:33], v[130:133], v[190:193], v[30:33]
	v_mfma_f32_16x16x32_bf16 v[26:29], v[138:141], v[190:193], v[26:29]
	v_mfma_f32_16x16x32_bf16 v[14:17], v[130:133], v[198:201], v[14:17]
	v_mfma_f32_16x16x32_bf16 v[10:13], v[138:141], v[198:201], v[10:13]
	v_mfma_f32_16x16x32_bf16 v[62:65], v[134:137], v[178:181], v[62:65]
	v_mfma_f32_16x16x32_bf16 v[58:61], v[142:145], v[178:181], v[58:61]
	v_mfma_f32_16x16x32_bf16 v[46:49], v[134:137], v[186:189], v[46:49]
	v_mfma_f32_16x16x32_bf16 v[42:45], v[142:145], v[186:189], v[42:45]
	v_mfma_f32_16x16x32_bf16 v[30:33], v[134:137], v[194:197], v[30:33]
	v_mfma_f32_16x16x32_bf16 v[26:29], v[142:145], v[194:197], v[26:29]
	v_mfma_f32_16x16x32_bf16 v[14:17], v[134:137], v[202:205], v[14:17]
	v_mfma_f32_16x16x32_bf16 v[10:13], v[142:145], v[202:205], v[10:13]
	s_setprio 0
	s_setprio 1
	v_mfma_f32_16x16x32_bf16 v[54:57], v[146:149], v[174:177], v[54:57]
	v_mfma_f32_16x16x32_bf16 v[50:53], v[166:169], v[174:177], v[50:53]
	v_mfma_f32_16x16x32_bf16 v[38:41], v[146:149], v[182:185], v[38:41]
	v_mfma_f32_16x16x32_bf16 v[34:37], v[166:169], v[182:185], v[34:37]
	v_mfma_f32_16x16x32_bf16 v[22:25], v[146:149], v[190:193], v[22:25]
	v_mfma_f32_16x16x32_bf16 v[18:21], v[166:169], v[190:193], v[18:21]
	v_mfma_f32_16x16x32_bf16 v[6:9], v[146:149], v[198:201], v[6:9]
	v_mfma_f32_16x16x32_bf16 v[2:5], v[166:169], v[198:201], v[2:5]
	v_mfma_f32_16x16x32_bf16 v[54:57], v[150:153], v[178:181], v[54:57]
	v_mfma_f32_16x16x32_bf16 v[50:53], v[170:173], v[178:181], v[50:53]
	v_mfma_f32_16x16x32_bf16 v[38:41], v[150:153], v[186:189], v[38:41]
	v_mfma_f32_16x16x32_bf16 v[34:37], v[170:173], v[186:189], v[34:37]
	v_mfma_f32_16x16x32_bf16 v[22:25], v[150:153], v[194:197], v[22:25]
	v_mfma_f32_16x16x32_bf16 v[18:21], v[170:173], v[194:197], v[18:21]
	v_mfma_f32_16x16x32_bf16 v[6:9], v[150:153], v[202:205], v[6:9]
	v_mfma_f32_16x16x32_bf16 v[2:5], v[170:173], v[202:205], v[2:5]
	s_setprio 0
	s_barrier
	s_add_i32 s67, s67, 2
	s_add_u32 s2, s2, 0x100
	s_addc_u32 s3, s3, 0
	s_add_u32 s65, s65, 0x100
	s_addc_u32 s66, s66, 0
	s_cmp_gt_u32 s67, 29
	s_cbranch_scc0 .LBB0_1855
	s_and_b64 vcc, exec, s[46:47]
	s_cbranch_vccz .LBB0_1858
	s_barrier
